# out GEMM layer-1 tail round: 4-way split-K sharing of the 16 leftover units (layer 0 unchanged since its tail hides weight conversion)
# baseline (speedup 1.0000x reference)
; #define LAS __attribute__((address_space(3)))
; __device__ __forceinline__ int opaque_tid(int wv) { asm volatile("" : "+s"(wv)); unsigned z = 0u; asm volatile("" : "+v"(z)); const int l = __builtin_amdgcn_mbcnt_hi(~0u, __builtin_amdgcn_mbcnt_lo(~0u, z)); return (wv << 6) | l; }
; template <class Epi, int LDA, int LDB, int KK>
; __device__ __forceinline__ void gemm_phase(int wv, LAS unsigned char* lds, const Gemm g, const StaticOrder& S, const Epi& E) {
;     const int tid = opaque_tid(wv), wid = __builtin_amdgcn_readfirstlane(tid >> 6), lane = tid & 63, wr = wid >> 2, wc = wid & 3, fr = lane & 15, fq = lane >> 4;
;     constexpr int nt = KK / BK;
;     unsigned voffA[2], voffB[2];
; #pragma unroll
;     for (int i = 0; i < 2; ++i) { int R, C; stage_rc(tid * 16 + i * 8192, R, C); const int Rb = (R & ~31) + perm32(R & 31);
;         voffA[i] = (unsigned)(R * LDA + C) * 2u; voffB[i] = (unsigned)(Rb * LDB + C) * 2u; }
;     constexpr size_t kstep = (size_t)(BK * 2);
;     constexpr size_t hstepA = (size_t)HALF * LDA * 2, hstepB = (size_t)HALF * LDB * 2;
;     constexpr size_t tstepA = 2 * hstepA, tstepB = 2 * hstepB;
;     const unsigned ldsw = (unsigned)wid * 1024u;
;     const int aoff = lds_byte(wr * 64 + fr, fq * 8), boff = lds_byte(wc * 32 + fr, fq * 8);
;     ...
;     Unit cur, nxt; int ui = 0;
;     if (!S.next(0, cur)) return;
;     f32x4 acc[2][2][4][2];
; #pragma unroll
;     for (int a = 0; a < 2; ++a)
; #pragma unroll
;         for (int b = 0; b < 2; ++b)
; #pragma unroll
;             for (int m = 0; m < 4; ++m)
; #pragma unroll
;                 for (int n = 0; n < 2; ++n) acc[a][b][m][n] = (f32x4){0.f, 0.f, 0.f, 0.f};
;     bf16x8 At[4][2], B0[2][2], B1[2][2];
;     const char* cA = (const char*)g.A + (size_t)cur.pm * tstepA; const char* cB = (const char*)g.Bt + (size_t)cur.pn * tstepB;
;     if constexpr (Epi::ROWSCALE) { if (wid < 4) __builtin_amdgcn_global_load_lds((const unsigned*)(E.rsq + cur.pm * 256 + wid * 64 + lane), (LAS unsigned*)(lds + 131072 + wid * 256), 4, 0, 0); }
;     PG8_STAGE(PG8_SB(0, 0), cB, voffB); PG8_STAGE(PG8_SA(0, 0), cA, voffA); PG8_STAGE(PG8_SB(0, 1), cB + hstepB, voffB); PG8_STAGE(PG8_SA(0, 1), cA + hstepA, voffA);
;     if (wr == 1) PG8_BAR;
;     PG8_WAIT_V(4); PG8_BAR;
;     PG8_STAGE(PG8_SB(1, 0), cB + kstep, voffB); PG8_STAGE(PG8_SA(1, 0), cA + kstep, voffA); PG8_STAGE(PG8_SB(1, 1), cB + hstepB + kstep, voffB);
.LBB0_614:
	s_or_b64 exec, exec, s[4:5]
	s_mov_b32 s100, 0
	s_mov_b32 s101, 0
	s_mov_b64 s[4:5], s[0:1]
	s_mov_b32 s30, s81
	s_mov_b32 s6, s95
	s_waitcnt lgkmcnt(0)
	v_mov_b32_e32 v0, v3
	s_barrier
	s_cmpk_gt_i32 s30, 0x20f
	v_mbcnt_lo_u32_b32 v0, -1, v0
	s_waitcnt vmcnt(2)
	v_mbcnt_hi_u32_b32 v18, -1, v0
	v_lshl_or_b32 v1, s6, 6, v18
	s_nop 0
	v_readfirstlane_b32 s31, v1
	s_cbranch_scc1 .LBB0_642
	v_lshlrev_b32_e32 v2, 4, v1
	v_add_u32_e32 v0, 0x2000, v2
	v_ashrrev_i32_e32 v4, 31, v0
	v_lshrrev_b32_e32 v4, 22, v4
	v_add_u32_e32 v4, v0, v4
	v_ashrrev_i32_e32 v12, 10, v4
	v_mul_i32_i24_e32 v4, 0x400, v12
	v_sub_u32_e32 v0, v0, v4
	v_lshrrev_b32_e32 v4, 4, v0
	v_bitop3_b32 v0, v4, v0, 32 bitop3:0x6c
	v_ashrrev_i32_e32 v4, 31, v0
	v_lshrrev_b32_e32 v4, 26, v4
	s_load_dwordx4 s[8:11], s[4:5], 0x98
	v_add_u32_e32 v4, v0, v4
	v_lshlrev_b32_e32 v5, 3, v12
	v_ashrrev_i32_e32 v13, 6, v4
	v_and_b32_e32 v5, -16, v5
	v_add_u32_e32 v5, v13, v5
	v_and_b32_e32 v6, 3, v13
	v_lshrrev_b32_e32 v7, 2, v5
	v_lshlrev_b32_e32 v8, 1, v5
	v_and_b32_e32 v4, 0xc0, v4
	v_and_or_b32 v6, v5, s86, v6
	v_and_b32_e32 v7, 4, v7
	v_and_b32_e32 v8, 24, v8
	v_sub_u32_e32 v0, v0, v4
	s_waitcnt lgkmcnt(0)
	s_add_u32 s34, s10, 0x8400000
	v_or3_b32 v6, v6, v7, v8
	v_lshlrev_b32_e32 v7, 5, v12
	v_ashrrev_i16_sdwa v0, v224, sext(v0) dst_sel:DWORD dst_unused:UNUSED_PAD src0_sel:DWORD src1_sel:BYTE_0
	s_addc_u32 s35, s11, 0
	v_and_b32_e32 v7, 32, v7
	v_bfe_i32 v14, v0, 0, 16
	s_add_u32 s36, s8, 0x4a00000
	v_add_lshl_u32 v4, v7, v14, 1
	s_addc_u32 s37, s9, 0
	v_lshl_add_u32 v0, v6, 12, v4
	v_lshl_add_u32 v188, v5, 12, v4
	v_bfe_i32 v4, v1, 27, 1
	s_ashr_i32 s39, s30, 31
	v_lshrrev_b32_e32 v4, 22, v4
	s_lshr_b32 s4, s39, 29
	v_add_u32_e32 v4, v2, v4
	s_add_i32 s4, s30, s4
	s_ashr_i32 s5, s31, 6
	v_and_b32_e32 v4, 0xfffffc00, v4
	s_ashr_i32 s7, s4, 3
	s_and_b32 s4, s4, -8
	s_ashr_i32 s6, s31, 8
	s_lshl_b32 s38, s5, 10
	v_sub_u32_e32 v2, v2, v4
	s_sub_i32 s4, s30, s4
	v_lshrrev_b32_e32 v4, 4, v2
	v_ashrrev_i32_e32 v5, 31, v1
	s_cmp_lt_i32 s4, 0
	s_movk_i32 s12, 0x43
	v_bitop3_b32 v2, v4, v2, 32 bitop3:0x6c
	v_lshrrev_b32_e32 v5, 26, v5
	s_cselect_b32 s12, s12, 0x42
	v_ashrrev_i32_e32 v4, 31, v2
	v_add_u32_e32 v1, v1, v5
	s_mul_i32 s4, s12, s4
	v_lshrrev_b32_e32 v4, 26, v4
	v_ashrrev_i32_e32 v16, 6, v1
	s_add_i32 s4, s4, s7
	v_add_u32_e32 v4, v2, v4
	v_lshlrev_b32_e32 v1, 3, v16
	s_ashr_i32 s7, s4, 31
	v_ashrrev_i32_e32 v15, 6, v4
	v_and_b32_e32 v1, -16, v1
	s_lshr_b32 s7, s7, 26
	v_add_u32_e32 v1, v15, v1
	s_add_i32 s7, s4, s7
	v_and_b32_e32 v5, 3, v15
	v_lshrrev_b32_e32 v6, 2, v1
	v_lshlrev_b32_e32 v7, 1, v1
	v_and_b32_e32 v4, 0xc0, v4
	s_ashr_i32 s12, s7, 6
	v_and_or_b32 v5, v1, s86, v5
	v_and_b32_e32 v6, 4, v6
	v_and_b32_e32 v7, 24, v7
	v_sub_u32_e32 v2, v2, v4
	s_lshl_b32 s14, s12, 3
	v_or3_b32 v5, v5, v6, v7
	v_lshlrev_b32_e32 v6, 5, v16
	v_ashrrev_i16_sdwa v2, v224, sext(v2) dst_sel:DWORD dst_unused:UNUSED_PAD src0_sel:DWORD src1_sel:BYTE_0
	s_sub_i32 s12, 0x42, s14
	v_and_b32_e32 v6, 32, v6
	v_bfe_i32 v17, v2, 0, 16
	s_min_u32 s15, s12, 8
	s_andn2_b32 s7, s7, 63
	v_add_lshl_u32 v4, v6, v17, 1
	s_sub_i32 s7, s4, s7
	v_cvt_f32_ubyte0_e32 v6, s15
	v_lshl_add_u32 v2, v5, 12, v4
	v_cvt_f32_i32_e32 v5, s7
	v_rcp_iflag_f32_e32 v7, v6
	v_lshl_add_u32 v190, v1, 12, v4
	s_ashr_i32 s4, s7, 30
	s_or_b32 s4, s4, 1
	v_mul_f32_e32 v1, v5, v7
	v_trunc_f32_e32 v1, v1
	v_fma_f32 v4, -v1, v6, v5
	v_cvt_i32_f32_e32 v1, v1
	v_cmp_ge_f32_e64 s[12:13], |v4|, v6
	s_and_b64 s[12:13], s[12:13], exec
	s_cselect_b32 s4, s4, 0
	v_readfirstlane_b32 s12, v1
	s_add_i32 s4, s12, s4
	s_mul_i32 s12, s4, s15
	s_sub_i32 s7, s7, s12
	s_sext_i32_i8 s7, s7
	s_add_i32 s22, s14, s7
	s_ashr_i32 s23, s22, 31
	s_bfe_i64 s[14:15], s[4:5], 0x80000
	s_lshl_b64 s[12:13], s[22:23], 20
	s_lshl_b64 s[14:15], s[14:15], 20
	s_add_u32 s24, s36, s14
	s_addc_u32 s25, s37, s15
	s_add_i32 s40, s38, 0
	s_add_i32 m0, s40, 0x10000
	v_mov_b32_e32 v1, v3
	global_load_lds_dwordx4 v2, s[24:25]
	s_add_i32 m0, s40, 0x12000
	s_add_u32 s26, s34, s12
	global_load_lds_dwordx4 v0, s[24:25]
	s_addc_u32 s27, s35, s13
	s_mov_b32 m0, s40
	s_add_i32 s41, s40, 0x2000
	global_load_lds_dwordx4 v190, s[26:27]
	s_mov_b32 m0, s41
	s_add_u32 s12, s24, 0x80000
	global_load_lds_dwordx4 v188, s[26:27]
	s_addc_u32 s13, s25, 0
	s_add_i32 m0, s40, 0x14000
	v_mov_b32_e32 v191, v3
	global_load_lds_dwordx4 v2, s[12:13]
	s_add_i32 m0, s40, 0x16000
	v_mov_b32_e32 v189, v3
	global_load_lds_dwordx4 v0, s[12:13]
	s_add_u32 s12, s26, 0x80000
	s_addc_u32 s13, s27, 0
	s_add_i32 s42, s40, 0x4000
	s_mov_b32 m0, s42
	s_add_i32 s43, s40, 0x6000
	global_load_lds_dwordx4 v190, s[12:13]
	s_mov_b32 m0, s43
	v_lshl_add_u64 v[10:11], s[24:25], 0, v[2:3]
	global_load_lds_dwordx4 v188, s[12:13]
	v_lshl_add_u64 v[8:9], s[24:25], 0, v[0:1]
	v_lshl_add_u64 v[6:7], s[26:27], 0, v[190:191]
	s_cmp_lg_u32 s6, 1
	v_lshl_add_u64 v[4:5], s[26:27], 0, v[188:189]
	s_cbranch_scc1 .LBB0_617

; #define LAS __attribute__((address_space(3)))
; template <class Epi, int LDA, int LDB, int KK>
; __device__ __forceinline__ void gemm_phase(int wv, LAS unsigned char* lds, const Gemm g, const StaticOrder& S, const Epi& E) {
;     ...
;     for (;;) {
;         const bool has_next = S.next(ui + 1, nxt);
;         const char* nA = has_next ? (const char*)g.A + (size_t)nxt.pm * tstepA : cA; const char* nB = has_next ? (const char*)g.Bt + (size_t)nxt.pn * tstepB : cB;
;         if constexpr (Epi::ROWSCALE) { if (has_next && wid < 4) __builtin_amdgcn_global_load_lds((const unsigned*)(E.rsq + nxt.pm * 256 + wid * 64 + lane), (LAS unsigned*)(lds + 131072 + ((ui + 1) % 3) * 1024 + wid * 256), 4, 0, 0); }
;         for (int seg = 0, t = 0; seg < Epi::NSEG; ++seg) {
;           const int tend = Epi::HAS_MID ? (seg == 0 ? Epi::MID1 : (seg == 1 ? Epi::MID2 : nt)) : nt;
;           for (; t < tend; t += 2) {
;             const bool last = (t == nt - 2);
;             const char* a1 = cA + (size_t)(t + 1) * kstep;
;             const char* a2 = last ? nA : cA + (size_t)(t + 2) * kstep; const char* b2 = last ? nB : cB + (size_t)(t + 2) * kstep;
;             const char* a3 = a2 + kstep; const char* b3 = b2 + kstep;
;             PG8_LDB(B0, 0, 0); PG8_SCHED; PG8_LDA(At, 0, 0); PG8_STAGE(PG8_SA(1, 1), a1 + hstepA, voffA);
;             PG8_WAIT_L(8); PG8_BAR; PG8_WAIT_L(0); PG8_MMA(0, 0, At, B0); PG8_BAR; PG8_SCHED;
;             PG8_LDB(B1, 0, 1); PG8_STAGE(PG8_SB(0, 0), b2, voffB);
;             PG8_BAR; PG8_WAIT_L(0); PG8_MMA(0, 1, At, B1); PG8_BAR;
;             PG8_LDA(At, 0, 1); PG8_STAGE(PG8_SA(0, 0), a2, voffA);
;             PG8_BAR; PG8_WAIT_L(0); PG8_MMA(1, 0, At, B0); PG8_BAR; PG8_SCHED;
;             PG8_STAGE(PG8_SB(0, 1), b2 + hstepB, voffB);
;             PG8_WAIT_V(6); PG8_BAR; PG8_MMA(1, 1, At, B1); PG8_BAR;
;             PG8_LDB(B0, 1, 0); PG8_SCHED; PG8_LDA(At, 1, 0); PG8_STAGE(PG8_SA(0, 1), a2 + hstepA, voffA);
;             PG8_WAIT_L(8); PG8_BAR; PG8_WAIT_L(0); PG8_MMA(0, 0, At, B0); PG8_BAR; PG8_SCHED;
;             PG8_LDB(B1, 1, 1); PG8_STAGE(PG8_SB(1, 0), b3, voffB);
;             PG8_BAR; PG8_WAIT_L(0); PG8_MMA(0, 1, At, B1); PG8_BAR;
;             PG8_LDA(At, 1, 1); PG8_STAGE(PG8_SA(1, 0), a3, voffA);
;             PG8_BAR; PG8_WAIT_L(0); PG8_MMA(1, 0, At, B0); PG8_BAR; PG8_SCHED;
;             PG8_STAGE(PG8_SB(1, 1), b3 + hstepB, voffB);
.LBB0_618:
	s_or_b64 exec, exec, s[22:23]
	s_mov_b32 s100, s101
	s_and_b64 vcc, exec, s[6:7]
	s_mov_b32 s23, s14
	s_mov_b32 s22, s16
	s_mov_b64 s[24:25], s[20:21]
	s_mov_b64 s[26:27], s[18:19]
	s_cbranch_vccnz .LBB0_639
.LBB0_619:
	s_add_i32 s46, s46, 1
	s_mul_i32 s6, s46, s49
	s_mul_hi_u32 s7, s46, s48
	s_add_i32 s7, s7, s6
	s_mul_i32 s6, s46, s48
	s_add_u32 s18, s6, s30
	s_addc_u32 s19, s7, s39
	s_mov_b32 s101, 0
	s_cmp_eq_u32 s2, 0
	s_cbranch_scc1 .Lot_h1
	s_cmp_lt_u32 s18, 0x200
	s_cbranch_scc1 .Lot_h1
	s_sub_u32 s98, s18, 0x200
	s_lshr_b32 s99, s98, 4
	s_and_b32 s98, s98, 15
	s_add_u32 s18, s98, 0x200
	s_add_u32 s101, s99, 1
	s_cmp_lt_u32 s99, 4
	s_cbranch_scc1 .Lot_h1
	s_movk_i32 s18, 0x210
	s_mov_b32 s101, 0
.Lot_h1:
	v_cmp_gt_i64_e64 s[6:7], s[18:19], v[198:199]
	s_and_b64 vcc, exec, s[6:7]
	s_cbranch_vccnz .LBB0_621
	s_ashr_i32 s14, s18, 31
	s_lshr_b32 s14, s14, 29
	s_add_i32 s14, s18, s14
	s_ashr_i32 s15, s14, 3
	s_and_b32 s14, s14, -8
	s_sub_i32 s14, s18, s14
	s_cmp_lt_i32 s14, 0
	s_movk_i32 s16, 0x43
	s_cselect_b32 s16, s16, 0x42
	s_mul_i32 s14, s16, s14
	s_add_i32 s14, s14, s15
	s_ashr_i32 s15, s14, 31
	s_lshr_b32 s15, s15, 26
	s_add_i32 s15, s14, s15
	s_ashr_i32 s16, s15, 6
	s_lshl_b32 s16, s16, 3
	s_sub_i32 s17, 0x42, s16
	s_min_i32 s17, s17, 8
	s_abs_i32 s20, s17
	v_cvt_f32_u32_e32 v4, s20
	s_sub_i32 s28, 0, s20
	s_andn2_b32 s15, s15, 63
	s_sub_i32 s15, s14, s15
	v_rcp_iflag_f32_e32 v4, v4
	s_abs_i32 s14, s15
	s_xor_b32 s21, s15, s17
	s_ashr_i32 s21, s21, 31
	v_mul_f32_e32 v4, 0x4f7ffffe, v4
	v_cvt_u32_f32_e32 v4, v4
	s_nop 0
	v_readfirstlane_b32 s29, v4
	s_mul_i32 s28, s28, s29
	s_mul_hi_u32 s28, s29, s28
	s_add_i32 s29, s29, s28
	s_mul_hi_u32 s28, s14, s29
	s_mul_i32 s29, s28, s20
	s_sub_i32 s14, s14, s29
	s_add_i32 s47, s28, 1
	s_sub_i32 s29, s14, s20
	s_cmp_ge_u32 s14, s20
	s_cselect_b32 s28, s47, s28
	s_cselect_b32 s14, s29, s14
	s_add_i32 s29, s28, 1
	s_cmp_ge_u32 s14, s20
	s_cselect_b32 s14, s29, s28
	s_xor_b32 s14, s14, s21
	s_sub_i32 s14, s14, s21
	s_mul_i32 s17, s14, s17
	s_sub_i32 s15, s15, s17
	s_add_i32 s16, s15, s16
.LBB0_621:
	s_ashr_i32 s17, s16, 31
	v_cmp_lt_i64_e32 vcc, s[18:19], v[200:201]
	s_lshl_b64 s[18:19], s[16:17], 20
	s_add_u32 s18, s34, s18
	s_addc_u32 s19, s35, s19
	s_and_b64 s[20:21], vcc, exec
	s_cselect_b32 s17, s19, s27
	s_cselect_b32 s47, s18, s26
	s_ashr_i32 s15, s14, 31
	s_lshl_b64 s[20:21], s[14:15], 20
	s_add_u32 s20, s36, s20
	s_addc_u32 s21, s37, s21
	s_and_b64 s[28:29], vcc, exec
	s_cselect_b32 s15, s21, s25
	s_cselect_b32 s55, s20, s24
	s_cmp_eq_u32 s101, 0
	s_cbranch_scc1 .Lot_h2
	s_sub_u32 s98, s101, 1
	s_lshl_b32 s98, s98, 10
	s_add_u32 s47, s47, s98
	s_addc_u32 s17, s17, 0
	s_add_u32 s55, s55, s98
	s_addc_u32 s15, s15, 0
	s_add_u32 s18, s18, s98
	s_addc_u32 s19, s19, 0
	s_add_u32 s20, s20, s98
	s_addc_u32 s21, s21, 0
.Lot_h2:
	s_add_u32 s56, s24, 0x100
	s_addc_u32 s68, s25, 0
	s_add_u32 s24, s26, 0x80080
	v_mov_b32_e32 v4, 0
	s_addc_u32 s25, s27, 0
	s_mov_b32 s69, -2
	s_cmp_eq_u32 s100, 0
	s_cselect_b32 s69, s69, 22
	s_waitcnt lgkmcnt(0)
	v_mov_b32_e32 v5, v4
	v_mov_b32_e32 v6, v4
	v_mov_b32_e32 v7, v4
	v_mov_b32_e32 v8, v4
	v_mov_b32_e32 v9, v4
	v_mov_b32_e32 v10, v4
	v_mov_b32_e32 v11, v4
	v_mov_b32_e32 v20, v4
	v_mov_b32_e32 v21, v4
	v_mov_b32_e32 v22, v4
	v_mov_b32_e32 v23, v4
	v_mov_b32_e32 v24, v4
	v_mov_b32_e32 v25, v4
	v_mov_b32_e32 v26, v4
	v_mov_b32_e32 v27, v4
	v_mov_b32_e32 v36, v4
	v_mov_b32_e32 v37, v4
	v_mov_b32_e32 v38, v4
	v_mov_b32_e32 v39, v4
	v_mov_b32_e32 v40, v4
	v_mov_b32_e32 v41, v4
	v_mov_b32_e32 v42, v4
	v_mov_b32_e32 v43, v4
	v_mov_b32_e32 v52, v4
	v_mov_b32_e32 v53, v4
	v_mov_b32_e32 v54, v4
	v_mov_b32_e32 v55, v4
	v_mov_b32_e32 v56, v4
	v_mov_b32_e32 v57, v4
	v_mov_b32_e32 v58, v4
	v_mov_b32_e32 v59, v4
	v_mov_b32_e32 v12, v4
	v_mov_b32_e32 v13, v4
	v_mov_b32_e32 v14, v4
	v_mov_b32_e32 v15, v4
	v_mov_b32_e32 v16, v4
	v_mov_b32_e32 v17, v4
	v_mov_b32_e32 v18, v4
	v_mov_b32_e32 v19, v4
	v_mov_b32_e32 v28, v4
	v_mov_b32_e32 v29, v4
	v_mov_b32_e32 v30, v4
	v_mov_b32_e32 v31, v4
	v_mov_b32_e32 v32, v4
	v_mov_b32_e32 v33, v4
	v_mov_b32_e32 v34, v4
	v_mov_b32_e32 v35, v4
	v_mov_b32_e32 v44, v4
	v_mov_b32_e32 v45, v4
	v_mov_b32_e32 v46, v4
	v_mov_b32_e32 v47, v4
	v_mov_b32_e32 v48, v4
	v_mov_b32_e32 v49, v4
	v_mov_b32_e32 v50, v4
	v_mov_b32_e32 v51, v4
	v_mov_b32_e32 v60, v4
	v_mov_b32_e32 v61, v4
	v_mov_b32_e32 v62, v4
	v_mov_b32_e32 v63, v4
	v_mov_b32_e32 v64, v4
	v_mov_b32_e32 v65, v4
	v_mov_b32_e32 v66, v4
	v_mov_b32_e32 v67, v4
	v_mov_b32_e32 v68, v4
	v_mov_b32_e32 v69, v4
	v_mov_b32_e32 v70, v4
	v_mov_b32_e32 v71, v4
	v_mov_b32_e32 v72, v4
	v_mov_b32_e32 v73, v4
	v_mov_b32_e32 v74, v4
	v_mov_b32_e32 v75, v4
	v_mov_b32_e32 v84, v4
	v_mov_b32_e32 v85, v4
	v_mov_b32_e32 v86, v4
	v_mov_b32_e32 v87, v4
	v_mov_b32_e32 v88, v4
	v_mov_b32_e32 v89, v4
	v_mov_b32_e32 v90, v4
	v_mov_b32_e32 v91, v4
	v_mov_b32_e32 v100, v4
	v_mov_b32_e32 v101, v4
	v_mov_b32_e32 v102, v4
	v_mov_b32_e32 v103, v4
	v_mov_b32_e32 v104, v4
	v_mov_b32_e32 v105, v4
	v_mov_b32_e32 v106, v4
	v_mov_b32_e32 v107, v4
	v_mov_b32_e32 v116, v4
	v_mov_b32_e32 v117, v4
	v_mov_b32_e32 v118, v4
	v_mov_b32_e32 v119, v4
	v_mov_b32_e32 v120, v4
	v_mov_b32_e32 v121, v4
	v_mov_b32_e32 v122, v4
	v_mov_b32_e32 v123, v4
	v_mov_b32_e32 v76, v4
	v_mov_b32_e32 v77, v4
	v_mov_b32_e32 v78, v4
	v_mov_b32_e32 v79, v4
	v_mov_b32_e32 v80, v4
	v_mov_b32_e32 v81, v4
	v_mov_b32_e32 v82, v4
	v_mov_b32_e32 v83, v4
	v_mov_b32_e32 v92, v4
	v_mov_b32_e32 v93, v4
	v_mov_b32_e32 v94, v4
	v_mov_b32_e32 v95, v4
	v_mov_b32_e32 v96, v4
	v_mov_b32_e32 v97, v4
	v_mov_b32_e32 v98, v4
	v_mov_b32_e32 v99, v4
	v_mov_b32_e32 v108, v4
	v_mov_b32_e32 v109, v4
	v_mov_b32_e32 v110, v4
	v_mov_b32_e32 v111, v4
	v_mov_b32_e32 v112, v4
	v_mov_b32_e32 v113, v4
	v_mov_b32_e32 v114, v4
	v_mov_b32_e32 v115, v4
	v_mov_b32_e32 v124, v4
	v_mov_b32_e32 v125, v4
	v_mov_b32_e32 v126, v4
	v_mov_b32_e32 v127, v4
	v_mov_b32_e32 v128, v4
	v_mov_b32_e32 v129, v4
	v_mov_b32_e32 v130, v4
	v_mov_b32_e32 v131, v4
	v_add_u32_e32 v180, 0x10000, v230
	ds_read_b128 v[132:135], v180 offset:0
	ds_read_b128 v[136:139], v180 offset:2048
	ds_read_b128 v[140:143], v180 offset:16384
	ds_read_b128 v[144:147], v180 offset:18432
	ds_read_b128 v[148:151], v234 offset:0
	ds_read_b128 v[152:155], v234 offset:2048
	ds_read_b128 v[156:159], v234 offset:4096
	ds_read_b128 v[160:163], v234 offset:6144
; #define PG8_STAGE(bufoff, gbase, voff) do { _Pragma("unroll") for (int _i = 0; _i < 2; ++_i) \
;         __builtin_amdgcn_global_load_lds((const unsigned*)((const char*)(gbase) + (voff)[_i]), (LAS unsigned*)(lds + (bufoff) + ldsw + _i * 8192), 16, 0, 0); } while (0)
; #define PG8_LDA(dst, b, h) do { _Pragma("unroll") for (int m = 0; m < 4; ++m) _Pragma("unroll") for (int k = 0; k < 2; ++k) dst[m][k] = *(const LAS bf16x8*)(lds + PG8_SA(b, h) + aoff + m * 2048 + k * 1024); } while (0)
; #define PG8_LDB(dst, b, h) do { _Pragma("unroll") for (int n = 0; n < 2; ++n) _Pragma("unroll") for (int k = 0; k < 2; ++k) dst[n][k] = *(const LAS bf16x8*)(lds + PG8_SB(b, h) + boff + n * 2048 + k * 1024); } while (0)
; #define PG8_MMA(ai, bj, At, Bt) do { __builtin_amdgcn_s_setprio(1); _Pragma("unroll") for (int m = 0; m < 4; ++m) _Pragma("unroll") for (int n = 0; n < 2; ++n) _Pragma("unroll") for (int k = 0; k < 2; ++k) \
;         acc[ai][bj][m][n] = __builtin_amdgcn_mfma_f32_16x16x32_bf16(Bt[n][k], At[m][k], acc[ai][bj][m][n], 0, 0, 0); __builtin_amdgcn_s_setprio(0); } while (0)
; #define PG8_WAIT_V(n) asm volatile("s_waitcnt vmcnt(" #n ")" ::: "memory")
; #define PG8_WAIT_L(n) asm volatile("s_waitcnt lgkmcnt(" #n ")" ::: "memory")
; template <class Epi, int LDA, int LDB, int KK>
; __device__ __forceinline__ void gemm_phase(int wv, LAS unsigned char* lds, const Gemm g, const StaticOrder& S, const Epi& E) {
;     ...
;           for (; t < tend; t += 2) {
;             const bool last = (t == nt - 2);
;             const char* a1 = cA + (size_t)(t + 1) * kstep;
;             const char* a2 = last ? nA : cA + (size_t)(t + 2) * kstep; const char* b2 = last ? nB : cB + (size_t)(t + 2) * kstep;
;             const char* a3 = a2 + kstep; const char* b3 = b2 + kstep;
;             PG8_LDB(B0, 0, 0); PG8_SCHED; PG8_LDA(At, 0, 0); PG8_STAGE(PG8_SA(1, 1), a1 + hstepA, voffA);
;             PG8_WAIT_L(8); PG8_BAR; PG8_WAIT_L(0); PG8_MMA(0, 0, At, B0); PG8_BAR; PG8_SCHED;
;             PG8_LDB(B1, 0, 1); PG8_STAGE(PG8_SB(0, 0), b2, voffB);
;             PG8_BAR; PG8_WAIT_L(0); PG8_MMA(0, 1, At, B1); PG8_BAR;
;             PG8_LDA(At, 0, 1); PG8_STAGE(PG8_SA(0, 0), a2, voffA);
;             PG8_BAR; PG8_WAIT_L(0); PG8_MMA(1, 0, At, B0); PG8_BAR; PG8_SCHED;
;             PG8_STAGE(PG8_SB(0, 1), b2 + hstepB, voffB);
;             PG8_WAIT_V(6); PG8_BAR; PG8_MMA(1, 1, At, B1); PG8_BAR;
.Lout_loop:
	s_add_u32 s26, s24, 0xfff80080
	s_addc_u32 s27, s25, -1
	s_cmp_eq_u32 s69, 28
	s_cselect_b32 s29, s17, s27
	s_cselect_b32 s28, s47, s26
	s_cselect_b32 s27, s15, s68
	s_cselect_b32 s26, s55, s56
	s_waitcnt lgkmcnt(0)
	v_mfma_f32_16x16x32_bf16 v[128:131], v[132:135], v[148:151], v[128:131]
	ds_read_b128 v[202:205], v180 offset:1024
	v_mfma_f32_16x16x32_bf16 v[124:127], v[136:139], v[148:151], v[124:127]
	ds_read_b128 v[206:209], v180 offset:3072
	v_mfma_f32_16x16x32_bf16 v[120:123], v[140:143], v[148:151], v[120:123]
	ds_read_b128 v[210:213], v180 offset:17408
	v_mfma_f32_16x16x32_bf16 v[116:119], v[144:147], v[148:151], v[116:119]
	ds_read_b128 v[214:217], v180 offset:19456
	v_mfma_f32_16x16x32_bf16 v[112:115], v[132:135], v[152:155], v[112:115]
	ds_read_b128 v[164:167], v234 offset:1024
	v_mfma_f32_16x16x32_bf16 v[108:111], v[136:139], v[152:155], v[108:111]
	ds_read_b128 v[168:171], v234 offset:3072
	v_mfma_f32_16x16x32_bf16 v[104:107], v[140:143], v[152:155], v[104:107]
	ds_read_b128 v[172:175], v234 offset:5120
	v_mfma_f32_16x16x32_bf16 v[100:103], v[144:147], v[152:155], v[100:103]
	ds_read_b128 v[176:179], v234 offset:7168
	v_mfma_f32_16x16x32_bf16 v[96:99], v[132:135], v[156:159], v[96:99]
	v_mfma_f32_16x16x32_bf16 v[92:95], v[136:139], v[156:159], v[92:95]
	v_mfma_f32_16x16x32_bf16 v[88:91], v[140:143], v[156:159], v[88:91]
	v_mfma_f32_16x16x32_bf16 v[84:87], v[144:147], v[156:159], v[84:87]
	v_mfma_f32_16x16x32_bf16 v[80:83], v[132:135], v[160:163], v[80:83]
	v_mfma_f32_16x16x32_bf16 v[76:79], v[136:139], v[160:163], v[76:79]
	v_mfma_f32_16x16x32_bf16 v[72:75], v[140:143], v[160:163], v[72:75]
	v_mfma_f32_16x16x32_bf16 v[68:71], v[144:147], v[160:163], v[68:71]
	s_waitcnt vmcnt(8) lgkmcnt(0)
	s_barrier
	v_mfma_f32_16x16x32_bf16 v[128:131], v[202:205], v[164:167], v[128:131]
	ds_read_b128 v[148:151], v234 offset:16384
	v_mfma_f32_16x16x32_bf16 v[124:127], v[206:209], v[164:167], v[124:127]
	ds_read_b128 v[152:155], v234 offset:18432
	v_mfma_f32_16x16x32_bf16 v[120:123], v[210:213], v[164:167], v[120:123]
	ds_read_b128 v[156:159], v234 offset:20480
	v_mfma_f32_16x16x32_bf16 v[116:119], v[214:217], v[164:167], v[116:119]
	ds_read_b128 v[160:163], v234 offset:22528
	v_mfma_f32_16x16x32_bf16 v[112:115], v[202:205], v[168:171], v[112:115]
	v_lshl_add_u64 v[182:183], s[26:27], 0, v[2:3]
	s_add_i32 m0, s40, 0x10000
	v_mfma_f32_16x16x32_bf16 v[108:111], v[206:209], v[168:171], v[108:111]
	global_load_lds_dwordx4 v[182:183], off
	v_mfma_f32_16x16x32_bf16 v[104:107], v[210:213], v[168:171], v[104:107]
	v_mfma_f32_16x16x32_bf16 v[100:103], v[214:217], v[168:171], v[100:103]
	v_lshl_add_u64 v[182:183], s[26:27], 0, v[0:1]
	s_add_i32 m0, s40, 0x12000
	v_mfma_f32_16x16x32_bf16 v[96:99], v[202:205], v[172:175], v[96:99]
	global_load_lds_dwordx4 v[182:183], off
	v_mfma_f32_16x16x32_bf16 v[92:95], v[206:209], v[172:175], v[92:95]
	v_mfma_f32_16x16x32_bf16 v[88:91], v[210:213], v[172:175], v[88:91]
	v_lshl_add_u64 v[182:183], s[28:29], 0, v[190:191]
	s_mov_b32 m0, s40
	v_mfma_f32_16x16x32_bf16 v[84:87], v[214:217], v[172:175], v[84:87]
	global_load_lds_dwordx4 v[182:183], off
	v_mfma_f32_16x16x32_bf16 v[80:83], v[202:205], v[176:179], v[80:83]
	v_mfma_f32_16x16x32_bf16 v[76:79], v[206:209], v[176:179], v[76:79]
	v_mfma_f32_16x16x32_bf16 v[72:75], v[210:213], v[176:179], v[72:75]
	v_mfma_f32_16x16x32_bf16 v[68:71], v[214:217], v[176:179], v[68:71]
	s_waitcnt lgkmcnt(0)
	v_mfma_f32_16x16x32_bf16 v[64:67], v[132:135], v[148:151], v[64:67]
	ds_read_b128 v[164:167], v234 offset:17408
	v_mfma_f32_16x16x32_bf16 v[60:63], v[136:139], v[148:151], v[60:63]
	ds_read_b128 v[168:171], v234 offset:19456
	v_mfma_f32_16x16x32_bf16 v[56:59], v[140:143], v[148:151], v[56:59]
	ds_read_b128 v[172:175], v234 offset:21504
	v_mfma_f32_16x16x32_bf16 v[52:55], v[144:147], v[148:151], v[52:55]
	ds_read_b128 v[176:179], v234 offset:23552
	v_mfma_f32_16x16x32_bf16 v[48:51], v[132:135], v[152:155], v[48:51]
	v_lshl_add_u64 v[182:183], s[28:29], 0, v[188:189]
	s_add_i32 m0, s40, 0x2000
	v_mfma_f32_16x16x32_bf16 v[44:47], v[136:139], v[152:155], v[44:47]
	global_load_lds_dwordx4 v[182:183], off
	v_mfma_f32_16x16x32_bf16 v[40:43], v[140:143], v[152:155], v[40:43]
	v_mfma_f32_16x16x32_bf16 v[36:39], v[144:147], v[152:155], v[36:39]
	s_add_u32 s98, s26, 0x80000
	s_addc_u32 s99, s27, 0
	v_lshl_add_u64 v[182:183], s[98:99], 0, v[2:3]
	s_add_i32 m0, s40, 0x14000
	v_mfma_f32_16x16x32_bf16 v[32:35], v[132:135], v[156:159], v[32:35]
	global_load_lds_dwordx4 v[182:183], off
	v_mfma_f32_16x16x32_bf16 v[28:31], v[136:139], v[156:159], v[28:31]
	v_mfma_f32_16x16x32_bf16 v[24:27], v[140:143], v[156:159], v[24:27]
	v_lshl_add_u64 v[182:183], s[98:99], 0, v[0:1]
	s_add_i32 m0, s40, 0x16000
	v_mfma_f32_16x16x32_bf16 v[20:23], v[144:147], v[156:159], v[20:23]
	global_load_lds_dwordx4 v[182:183], off
	v_mfma_f32_16x16x32_bf16 v[16:19], v[132:135], v[160:163], v[16:19]
	v_mfma_f32_16x16x32_bf16 v[12:15], v[136:139], v[160:163], v[12:15]
	v_mfma_f32_16x16x32_bf16 v[8:11], v[140:143], v[160:163], v[8:11]
	v_mfma_f32_16x16x32_bf16 v[4:7], v[144:147], v[160:163], v[4:7]
	s_waitcnt vmcnt(8) lgkmcnt(0)
	s_barrier
; #define PG8_STAGE(bufoff, gbase, voff) do { _Pragma("unroll") for (int _i = 0; _i < 2; ++_i) \
;         __builtin_amdgcn_global_load_lds((const unsigned*)((const char*)(gbase) + (voff)[_i]), (LAS unsigned*)(lds + (bufoff) + ldsw + _i * 8192), 16, 0, 0); } while (0)
; #define PG8_LDA(dst, b, h) do { _Pragma("unroll") for (int m = 0; m < 4; ++m) _Pragma("unroll") for (int k = 0; k < 2; ++k) dst[m][k] = *(const LAS bf16x8*)(lds + PG8_SA(b, h) + aoff + m * 2048 + k * 1024); } while (0)
; #define PG8_LDB(dst, b, h) do { _Pragma("unroll") for (int n = 0; n < 2; ++n) _Pragma("unroll") for (int k = 0; k < 2; ++k) dst[n][k] = *(const LAS bf16x8*)(lds + PG8_SB(b, h) + boff + n * 2048 + k * 1024); } while (0)
; #define PG8_MMA(ai, bj, At, Bt) do { __builtin_amdgcn_s_setprio(1); _Pragma("unroll") for (int m = 0; m < 4; ++m) _Pragma("unroll") for (int n = 0; n < 2; ++n) _Pragma("unroll") for (int k = 0; k < 2; ++k) \
;         acc[ai][bj][m][n] = __builtin_amdgcn_mfma_f32_16x16x32_bf16(Bt[n][k], At[m][k], acc[ai][bj][m][n], 0, 0, 0); __builtin_amdgcn_s_setprio(0); } while (0)
; #define PG8_WAIT_V(n) asm volatile("s_waitcnt vmcnt(" #n ")" ::: "memory")
; #define PG8_WAIT_L(n) asm volatile("s_waitcnt lgkmcnt(" #n ")" ::: "memory")
; #define PG8_BAR __builtin_amdgcn_s_barrier()
; #define PG8_SCHED __builtin_amdgcn_sched_barrier(0)
; template <class Epi, int LDA, int LDB, int KK>
; __device__ __forceinline__ void gemm_phase(int wv, LAS unsigned char* lds, const Gemm g, const StaticOrder& S, const Epi& E) {
;     ...
;             PG8_WAIT_V(6); PG8_BAR; PG8_MMA(1, 1, At, B1); PG8_BAR;
;             PG8_LDB(B0, 1, 0); PG8_SCHED; PG8_LDA(At, 1, 0); PG8_STAGE(PG8_SA(0, 1), a2 + hstepA, voffA);
;             PG8_WAIT_L(8); PG8_BAR; PG8_WAIT_L(0); PG8_MMA(0, 0, At, B0); PG8_BAR; PG8_SCHED;
;             PG8_LDB(B1, 1, 1); PG8_STAGE(PG8_SB(1, 0), b3, voffB);
;             PG8_BAR; PG8_WAIT_L(0); PG8_MMA(0, 1, At, B1); PG8_BAR;
;             PG8_LDA(At, 1, 1); PG8_STAGE(PG8_SA(1, 0), a3, voffA);
;             PG8_BAR; PG8_WAIT_L(0); PG8_MMA(1, 0, At, B0); PG8_BAR; PG8_SCHED;
;             PG8_STAGE(PG8_SB(1, 1), b3 + hstepB, voffB);
;             PG8_WAIT_V(6); PG8_BAR; PG8_MMA(1, 1, At, B1); PG8_BAR;
	v_mfma_f32_16x16x32_bf16 v[64:67], v[202:205], v[164:167], v[64:67]
	ds_read_b128 v[132:135], v180 offset:32768
	v_mfma_f32_16x16x32_bf16 v[60:63], v[206:209], v[164:167], v[60:63]
	ds_read_b128 v[136:139], v180 offset:34816
	v_mfma_f32_16x16x32_bf16 v[56:59], v[210:213], v[164:167], v[56:59]
	ds_read_b128 v[140:143], v180 offset:49152
	v_mfma_f32_16x16x32_bf16 v[52:55], v[214:217], v[164:167], v[52:55]
	ds_read_b128 v[144:147], v180 offset:51200
	v_mfma_f32_16x16x32_bf16 v[48:51], v[202:205], v[168:171], v[48:51]
	ds_read_b128 v[148:151], v234 offset:32768
	v_mfma_f32_16x16x32_bf16 v[44:47], v[206:209], v[168:171], v[44:47]
	ds_read_b128 v[152:155], v234 offset:34816
	v_mfma_f32_16x16x32_bf16 v[40:43], v[210:213], v[168:171], v[40:43]
	ds_read_b128 v[156:159], v234 offset:36864
	v_mfma_f32_16x16x32_bf16 v[36:39], v[214:217], v[168:171], v[36:39]
	ds_read_b128 v[160:163], v234 offset:38912
	v_mfma_f32_16x16x32_bf16 v[32:35], v[202:205], v[172:175], v[32:35]
	s_add_u32 s98, s28, 0x80000
	s_addc_u32 s99, s29, 0
	v_lshl_add_u64 v[182:183], s[98:99], 0, v[190:191]
	s_add_i32 m0, s40, 0x4000
	v_mfma_f32_16x16x32_bf16 v[28:31], v[206:209], v[172:175], v[28:31]
	global_load_lds_dwordx4 v[182:183], off
	v_mfma_f32_16x16x32_bf16 v[24:27], v[210:213], v[172:175], v[24:27]
	v_mfma_f32_16x16x32_bf16 v[20:23], v[214:217], v[172:175], v[20:23]
	v_lshl_add_u64 v[182:183], s[98:99], 0, v[188:189]
	s_add_i32 m0, s40, 0x6000
	v_mfma_f32_16x16x32_bf16 v[16:19], v[202:205], v[176:179], v[16:19]
	global_load_lds_dwordx4 v[182:183], off
	v_mfma_f32_16x16x32_bf16 v[12:15], v[206:209], v[176:179], v[12:15]
	v_mfma_f32_16x16x32_bf16 v[8:11], v[210:213], v[176:179], v[8:11]
	v_mfma_f32_16x16x32_bf16 v[4:7], v[214:217], v[176:179], v[4:7]
	s_add_u32 s26, s26, 0x80
	s_addc_u32 s27, s27, 0
	s_add_u32 s28, s28, 0x80
	s_addc_u32 s29, s29, 0
	s_waitcnt lgkmcnt(0)
	v_mfma_f32_16x16x32_bf16 v[128:131], v[132:135], v[148:151], v[128:131]
	ds_read_b128 v[202:205], v180 offset:33792
	v_mfma_f32_16x16x32_bf16 v[124:127], v[136:139], v[148:151], v[124:127]
	ds_read_b128 v[206:209], v180 offset:35840
	v_mfma_f32_16x16x32_bf16 v[120:123], v[140:143], v[148:151], v[120:123]
	ds_read_b128 v[210:213], v180 offset:50176
	v_mfma_f32_16x16x32_bf16 v[116:119], v[144:147], v[148:151], v[116:119]
	ds_read_b128 v[214:217], v180 offset:52224
	v_mfma_f32_16x16x32_bf16 v[112:115], v[132:135], v[152:155], v[112:115]
	ds_read_b128 v[164:167], v234 offset:33792
	v_mfma_f32_16x16x32_bf16 v[108:111], v[136:139], v[152:155], v[108:111]
	ds_read_b128 v[168:171], v234 offset:35840
	v_mfma_f32_16x16x32_bf16 v[104:107], v[140:143], v[152:155], v[104:107]
	ds_read_b128 v[172:175], v234 offset:37888
	v_mfma_f32_16x16x32_bf16 v[100:103], v[144:147], v[152:155], v[100:103]
	ds_read_b128 v[176:179], v234 offset:39936
	v_mfma_f32_16x16x32_bf16 v[96:99], v[132:135], v[156:159], v[96:99]
	v_mfma_f32_16x16x32_bf16 v[92:95], v[136:139], v[156:159], v[92:95]
	v_mfma_f32_16x16x32_bf16 v[88:91], v[140:143], v[156:159], v[88:91]
	v_mfma_f32_16x16x32_bf16 v[84:87], v[144:147], v[156:159], v[84:87]
	v_mfma_f32_16x16x32_bf16 v[80:83], v[132:135], v[160:163], v[80:83]
	v_mfma_f32_16x16x32_bf16 v[76:79], v[136:139], v[160:163], v[76:79]
	v_mfma_f32_16x16x32_bf16 v[72:75], v[140:143], v[160:163], v[72:75]
	v_mfma_f32_16x16x32_bf16 v[68:71], v[144:147], v[160:163], v[68:71]
	s_waitcnt vmcnt(8) lgkmcnt(0)
	s_barrier
	v_mfma_f32_16x16x32_bf16 v[128:131], v[202:205], v[164:167], v[128:131]
	ds_read_b128 v[148:151], v234 offset:49152
	v_mfma_f32_16x16x32_bf16 v[124:127], v[206:209], v[164:167], v[124:127]
	ds_read_b128 v[152:155], v234 offset:51200
	v_mfma_f32_16x16x32_bf16 v[120:123], v[210:213], v[164:167], v[120:123]
	ds_read_b128 v[156:159], v234 offset:53248
	v_mfma_f32_16x16x32_bf16 v[116:119], v[214:217], v[164:167], v[116:119]
	ds_read_b128 v[160:163], v234 offset:55296
	v_mfma_f32_16x16x32_bf16 v[112:115], v[202:205], v[168:171], v[112:115]
	v_lshl_add_u64 v[182:183], s[26:27], 0, v[2:3]
	s_add_i32 m0, s40, 0x18000
	v_mfma_f32_16x16x32_bf16 v[108:111], v[206:209], v[168:171], v[108:111]
	global_load_lds_dwordx4 v[182:183], off
	v_mfma_f32_16x16x32_bf16 v[104:107], v[210:213], v[168:171], v[104:107]
	v_mfma_f32_16x16x32_bf16 v[100:103], v[214:217], v[168:171], v[100:103]
	v_lshl_add_u64 v[182:183], s[26:27], 0, v[0:1]
	s_add_i32 m0, s40, 0x1a000
	v_mfma_f32_16x16x32_bf16 v[96:99], v[202:205], v[172:175], v[96:99]
	global_load_lds_dwordx4 v[182:183], off
	v_mfma_f32_16x16x32_bf16 v[92:95], v[206:209], v[172:175], v[92:95]
	v_mfma_f32_16x16x32_bf16 v[88:91], v[210:213], v[172:175], v[88:91]
	v_lshl_add_u64 v[182:183], s[28:29], 0, v[190:191]
	s_add_i32 m0, s40, 0x8000
	v_mfma_f32_16x16x32_bf16 v[84:87], v[214:217], v[172:175], v[84:87]
	global_load_lds_dwordx4 v[182:183], off
	v_mfma_f32_16x16x32_bf16 v[80:83], v[202:205], v[176:179], v[80:83]
	v_mfma_f32_16x16x32_bf16 v[76:79], v[206:209], v[176:179], v[76:79]
	v_mfma_f32_16x16x32_bf16 v[72:75], v[210:213], v[176:179], v[72:75]
	v_mfma_f32_16x16x32_bf16 v[68:71], v[214:217], v[176:179], v[68:71]
	s_waitcnt lgkmcnt(0)
	v_mfma_f32_16x16x32_bf16 v[64:67], v[132:135], v[148:151], v[64:67]
	ds_read_b128 v[164:167], v234 offset:50176
	v_mfma_f32_16x16x32_bf16 v[60:63], v[136:139], v[148:151], v[60:63]
	ds_read_b128 v[168:171], v234 offset:52224
	v_mfma_f32_16x16x32_bf16 v[56:59], v[140:143], v[148:151], v[56:59]
	ds_read_b128 v[172:175], v234 offset:54272
	v_mfma_f32_16x16x32_bf16 v[52:55], v[144:147], v[148:151], v[52:55]
	ds_read_b128 v[176:179], v234 offset:56320
	v_mfma_f32_16x16x32_bf16 v[48:51], v[132:135], v[152:155], v[48:51]
	v_lshl_add_u64 v[182:183], s[28:29], 0, v[188:189]
	s_add_i32 m0, s40, 0xa000
	v_mfma_f32_16x16x32_bf16 v[44:47], v[136:139], v[152:155], v[44:47]
	global_load_lds_dwordx4 v[182:183], off
	v_mfma_f32_16x16x32_bf16 v[40:43], v[140:143], v[152:155], v[40:43]
	v_mfma_f32_16x16x32_bf16 v[36:39], v[144:147], v[152:155], v[36:39]
	s_add_u32 s98, s26, 0x80000
	s_addc_u32 s99, s27, 0
	v_lshl_add_u64 v[182:183], s[98:99], 0, v[2:3]
	s_add_i32 m0, s40, 0x1c000
	v_mfma_f32_16x16x32_bf16 v[32:35], v[132:135], v[156:159], v[32:35]
	global_load_lds_dwordx4 v[182:183], off
	v_mfma_f32_16x16x32_bf16 v[28:31], v[136:139], v[156:159], v[28:31]
	v_mfma_f32_16x16x32_bf16 v[24:27], v[140:143], v[156:159], v[24:27]
	v_lshl_add_u64 v[182:183], s[98:99], 0, v[0:1]
	s_add_i32 m0, s40, 0x1e000
	v_mfma_f32_16x16x32_bf16 v[20:23], v[144:147], v[156:159], v[20:23]
	global_load_lds_dwordx4 v[182:183], off
	v_mfma_f32_16x16x32_bf16 v[16:19], v[132:135], v[160:163], v[16:19]
	v_mfma_f32_16x16x32_bf16 v[12:15], v[136:139], v[160:163], v[12:15]
	v_mfma_f32_16x16x32_bf16 v[8:11], v[140:143], v[160:163], v[8:11]
	v_mfma_f32_16x16x32_bf16 v[4:7], v[144:147], v[160:163], v[4:7]
	s_waitcnt vmcnt(8) lgkmcnt(0)
	s_barrier
; #define LAS __attribute__((address_space(3)))
; #define PG8_STAGE(bufoff, gbase, voff) do { _Pragma("unroll") for (int _i = 0; _i < 2; ++_i) \
;         __builtin_amdgcn_global_load_lds((const unsigned*)((const char*)(gbase) + (voff)[_i]), (LAS unsigned*)(lds + (bufoff) + ldsw + _i * 8192), 16, 0, 0); } while (0)
; #define PG8_MMA(ai, bj, At, Bt) do { __builtin_amdgcn_s_setprio(1); _Pragma("unroll") for (int m = 0; m < 4; ++m) _Pragma("unroll") for (int n = 0; n < 2; ++n) _Pragma("unroll") for (int k = 0; k < 2; ++k) \
;         acc[ai][bj][m][n] = __builtin_amdgcn_mfma_f32_16x16x32_bf16(Bt[n][k], At[m][k], acc[ai][bj][m][n], 0, 0, 0); __builtin_amdgcn_s_setprio(0); } while (0)
; #define PG8_WAIT_V(n) asm volatile("s_waitcnt vmcnt(" #n ")" ::: "memory")
; #define PG8_WAIT_L(n) asm volatile("s_waitcnt lgkmcnt(" #n ")" ::: "memory")
; #define PG8_BAR __builtin_amdgcn_s_barrier()
; #define PG8_SCHED __builtin_amdgcn_sched_barrier(0)
; template <class Epi, int LDA, int LDB, int KK>
; __device__ __forceinline__ void gemm_phase(int wv, LAS unsigned char* lds, const Gemm g, const StaticOrder& S, const Epi& E) {
;     ...
;             PG8_BAR; PG8_WAIT_L(0); PG8_MMA(1, 0, At, B0); PG8_BAR; PG8_SCHED;
;             PG8_STAGE(PG8_SB(1, 1), b3 + hstepB, voffB);
;             PG8_WAIT_V(6); PG8_BAR; PG8_MMA(1, 1, At, B1); PG8_BAR;
;           }
;           if constexpr (Epi::HAS_MID) { if (seg < Epi::NSEG - 1) E.mid(acc, cur, seg, wr, wc, fr, fq); }
;         }
;         E(acc, cur, wr, wc, fr, fq, (const LAS float*)(lds + 131072 + (ui % 3) * 1024));
	v_mfma_f32_16x16x32_bf16 v[64:67], v[202:205], v[164:167], v[64:67]
	ds_read_b128 v[132:135], v180 offset:0
	v_mfma_f32_16x16x32_bf16 v[60:63], v[206:209], v[164:167], v[60:63]
	ds_read_b128 v[136:139], v180 offset:2048
	v_mfma_f32_16x16x32_bf16 v[56:59], v[210:213], v[164:167], v[56:59]
	ds_read_b128 v[140:143], v180 offset:16384
	v_mfma_f32_16x16x32_bf16 v[52:55], v[214:217], v[164:167], v[52:55]
	ds_read_b128 v[144:147], v180 offset:18432
	v_mfma_f32_16x16x32_bf16 v[48:51], v[202:205], v[168:171], v[48:51]
	ds_read_b128 v[148:151], v234 offset:0
	v_mfma_f32_16x16x32_bf16 v[44:47], v[206:209], v[168:171], v[44:47]
	ds_read_b128 v[152:155], v234 offset:2048
	v_mfma_f32_16x16x32_bf16 v[40:43], v[210:213], v[168:171], v[40:43]
	ds_read_b128 v[156:159], v234 offset:4096
	v_mfma_f32_16x16x32_bf16 v[36:39], v[214:217], v[168:171], v[36:39]
	ds_read_b128 v[160:163], v234 offset:6144
	v_mfma_f32_16x16x32_bf16 v[32:35], v[202:205], v[172:175], v[32:35]
	s_add_u32 s98, s28, 0x80000
	s_addc_u32 s99, s29, 0
	v_lshl_add_u64 v[182:183], s[98:99], 0, v[190:191]
	s_add_i32 m0, s40, 0xc000
	v_mfma_f32_16x16x32_bf16 v[28:31], v[206:209], v[172:175], v[28:31]
	global_load_lds_dwordx4 v[182:183], off
	v_mfma_f32_16x16x32_bf16 v[24:27], v[210:213], v[172:175], v[24:27]
	v_mfma_f32_16x16x32_bf16 v[20:23], v[214:217], v[172:175], v[20:23]
	v_lshl_add_u64 v[182:183], s[98:99], 0, v[188:189]
	s_add_i32 m0, s40, 0xe000
	v_mfma_f32_16x16x32_bf16 v[16:19], v[202:205], v[176:179], v[16:19]
	global_load_lds_dwordx4 v[182:183], off
	v_mfma_f32_16x16x32_bf16 v[12:15], v[206:209], v[176:179], v[12:15]
	v_mfma_f32_16x16x32_bf16 v[8:11], v[210:213], v[176:179], v[8:11]
	v_mfma_f32_16x16x32_bf16 v[4:7], v[214:217], v[176:179], v[4:7]
	s_add_i32 s69, s69, 2
	s_add_u32 s56, s56, 0x100
	s_addc_u32 s68, s68, 0
	s_add_u32 s24, s24, 0x100
	s_addc_u32 s25, s25, 0
	s_cmp_gt_u32 s69, 29
	s_cbranch_scc0 .Lout_loop
	s_waitcnt lgkmcnt(0)
	s_cmp_eq_u32 s100, 0
	s_cbranch_scc1 .Lot_epi
	s_cmp_eq_u32 s100, 4
	s_cbranch_scc1 .Lot_owner
	s_and_b32 s98, s81, 15
	s_mul_i32 s98, s98, 3
	s_add_u32 s98, s98, s100
	s_sub_u32 s98, s98, 1
	s_lshl_b32 s98, s98, 18
	s_add_u32 s98, s98, 0x1f000000
	s_add_u32 s98, s10, s98
	s_addc_u32 s99, s11, 0
	v_mbcnt_lo_u32_b32 v132, -1, 0
	v_mbcnt_hi_u32_b32 v132, -1, v132
	v_lshl_or_b32 v132, s95, 6, v132
	v_lshlrev_b32_e32 v132, 4, v132
	global_store_dwordx4 v132, v[4:7], s[98:99] sc0 sc1
	v_add_u32_e32 v132, 0x2000, v132
	global_store_dwordx4 v132, v[8:11], s[98:99] sc0 sc1
	v_add_u32_e32 v132, 0x2000, v132
	global_store_dwordx4 v132, v[12:15], s[98:99] sc0 sc1
	v_add_u32_e32 v132, 0x2000, v132
	global_store_dwordx4 v132, v[16:19], s[98:99] sc0 sc1
	v_add_u32_e32 v132, 0x2000, v132
	global_store_dwordx4 v132, v[20:23], s[98:99] sc0 sc1
	v_add_u32_e32 v132, 0x2000, v132
	global_store_dwordx4 v132, v[24:27], s[98:99] sc0 sc1
	v_add_u32_e32 v132, 0x2000, v132
	global_store_dwordx4 v132, v[28:31], s[98:99] sc0 sc1
	v_add_u32_e32 v132, 0x2000, v132
	global_store_dwordx4 v132, v[32:35], s[98:99] sc0 sc1
	v_add_u32_e32 v132, 0x2000, v132
	global_store_dwordx4 v132, v[36:39], s[98:99] sc0 sc1
	v_add_u32_e32 v132, 0x2000, v132
	global_store_dwordx4 v132, v[40:43], s[98:99] sc0 sc1
	v_add_u32_e32 v132, 0x2000, v132
	global_store_dwordx4 v132, v[44:47], s[98:99] sc0 sc1
	v_add_u32_e32 v132, 0x2000, v132
	global_store_dwordx4 v132, v[48:51], s[98:99] sc0 sc1
	v_add_u32_e32 v132, 0x2000, v132
	global_store_dwordx4 v132, v[52:55], s[98:99] sc0 sc1
	v_add_u32_e32 v132, 0x2000, v132
	global_store_dwordx4 v132, v[56:59], s[98:99] sc0 sc1
	v_add_u32_e32 v132, 0x2000, v132
	global_store_dwordx4 v132, v[60:63], s[98:99] sc0 sc1
	v_add_u32_e32 v132, 0x2000, v132
	global_store_dwordx4 v132, v[64:67], s[98:99] sc0 sc1
	v_add_u32_e32 v132, 0x2000, v132
	global_store_dwordx4 v132, v[68:71], s[98:99] sc0 sc1
	v_add_u32_e32 v132, 0x2000, v132
	global_store_dwordx4 v132, v[72:75], s[98:99] sc0 sc1
	v_add_u32_e32 v132, 0x2000, v132
	global_store_dwordx4 v132, v[76:79], s[98:99] sc0 sc1
	v_add_u32_e32 v132, 0x2000, v132
	global_store_dwordx4 v132, v[80:83], s[98:99] sc0 sc1
	v_add_u32_e32 v132, 0x2000, v132
	global_store_dwordx4 v132, v[84:87], s[98:99] sc0 sc1
	v_add_u32_e32 v132, 0x2000, v132
	global_store_dwordx4 v132, v[88:91], s[98:99] sc0 sc1
	v_add_u32_e32 v132, 0x2000, v132
	global_store_dwordx4 v132, v[92:95], s[98:99] sc0 sc1
	v_add_u32_e32 v132, 0x2000, v132
	global_store_dwordx4 v132, v[96:99], s[98:99] sc0 sc1
	v_add_u32_e32 v132, 0x2000, v132
	global_store_dwordx4 v132, v[100:103], s[98:99] sc0 sc1
	v_add_u32_e32 v132, 0x2000, v132
	global_store_dwordx4 v132, v[104:107], s[98:99] sc0 sc1
	v_add_u32_e32 v132, 0x2000, v132
	global_store_dwordx4 v132, v[108:111], s[98:99] sc0 sc1
	v_add_u32_e32 v132, 0x2000, v132
	global_store_dwordx4 v132, v[112:115], s[98:99] sc0 sc1
	v_add_u32_e32 v132, 0x2000, v132
	global_store_dwordx4 v132, v[116:119], s[98:99] sc0 sc1
	v_add_u32_e32 v132, 0x2000, v132
	global_store_dwordx4 v132, v[120:123], s[98:99] sc0 sc1
	v_add_u32_e32 v132, 0x2000, v132
	global_store_dwordx4 v132, v[124:127], s[98:99] sc0 sc1
	v_add_u32_e32 v132, 0x2000, v132
	global_store_dwordx4 v132, v[128:131], s[98:99] sc0 sc1
	s_waitcnt vmcnt(0)
	s_barrier
	s_cmp_lg_u32 s95, 0
	s_cbranch_scc1 .Lot_p_done
	s_and_b32 s98, s81, 15
	s_lshl_b32 s98, s98, 2
	s_add_u32 s98, s98, 0x285da940
	s_add_u32 s98, s10, s98
	s_addc_u32 s99, s11, 0
	s_mov_b64 exec, 1
	v_mov_b32_e32 v132, 0
	v_mov_b32_e32 v133, 1
	global_atomic_add v132, v133, s[98:99]
	s_mov_b64 exec, -1

; #define LAS __attribute__((address_space(3)))
; template <class Epi, int LDA, int LDB, int KK>
; __device__ __forceinline__ void gemm_phase(int wv, LAS unsigned char* lds, const Gemm g, const StaticOrder& S, const Epi& E) {
;     ...
;         E(acc, cur, wr, wc, fr, fq, (const LAS float*)(lds + 131072 + (ui % 3) * 1024));
.Lot_owner:
	s_cmp_lg_u32 s95, 0
	s_cbranch_scc1 .Lot_o_wait
	s_and_b32 s98, s81, 15
	s_lshl_b32 s98, s98, 2
	s_add_u32 s98, s98, 0x285da940
	s_add_u32 s98, s10, s98
	s_addc_u32 s99, s11, 0
	s_mov_b32 s100, 3
	s_nop 0
	s_mov_b64 exec, 1
	v_mov_b32_e32 v132, 0

; #define LAS __attribute__((address_space(3)))
; template <class Epi, int LDA, int LDB, int KK>
; __device__ __forceinline__ void gemm_phase(int wv, LAS unsigned char* lds, const Gemm g, const StaticOrder& S, const Epi& E) {
;     ...
;         E(acc, cur, wr, wc, fr, fq, (const LAS float*)(lds + 131072 + (ui % 3) * 1024));
.Lot_o_wait:
	s_barrier
	s_and_b32 s98, s81, 15
	s_mul_i32 s98, s98, 3
	s_lshl_b32 s98, s98, 18
	s_add_u32 s98, s98, 0x1f000000
	s_add_u32 s98, s10, s98
	s_addc_u32 s99, s11, 0
	v_mbcnt_lo_u32_b32 v132, -1, 0
	v_mbcnt_hi_u32_b32 v132, -1, v132
	v_lshl_or_b32 v132, s95, 6, v132
	v_lshlrev_b32_e32 v132, 4, v132
	global_load_dwordx4 v[136:139], v132, s[98:99] sc0 sc1
	v_add_u32_e32 v132, 0x2000, v132
	global_load_dwordx4 v[140:143], v132, s[98:99] sc0 sc1
	v_add_u32_e32 v132, 0x2000, v132
	global_load_dwordx4 v[144:147], v132, s[98:99] sc0 sc1
	v_add_u32_e32 v132, 0x2000, v132
	global_load_dwordx4 v[148:151], v132, s[98:99] sc0 sc1
	v_add_u32_e32 v132, 0x2000, v132
	global_load_dwordx4 v[152:155], v132, s[98:99] sc0 sc1
	v_add_u32_e32 v132, 0x2000, v132
	global_load_dwordx4 v[156:159], v132, s[98:99] sc0 sc1
	v_add_u32_e32 v132, 0x2000, v132
	global_load_dwordx4 v[160:163], v132, s[98:99] sc0 sc1
	v_add_u32_e32 v132, 0x2000, v132
	global_load_dwordx4 v[164:167], v132, s[98:99] sc0 sc1
	v_add_u32_e32 v132, 0x2000, v132
	s_waitcnt vmcnt(7)
	v_pk_add_f32 v[4:5], v[4:5], v[136:137]
	v_pk_add_f32 v[6:7], v[6:7], v[138:139]
	s_waitcnt vmcnt(6)
	v_pk_add_f32 v[8:9], v[8:9], v[140:141]
	v_pk_add_f32 v[10:11], v[10:11], v[142:143]
	s_waitcnt vmcnt(5)
	v_pk_add_f32 v[12:13], v[12:13], v[144:145]
	v_pk_add_f32 v[14:15], v[14:15], v[146:147]
	s_waitcnt vmcnt(4)
	v_pk_add_f32 v[16:17], v[16:17], v[148:149]
	v_pk_add_f32 v[18:19], v[18:19], v[150:151]
	s_waitcnt vmcnt(3)
	v_pk_add_f32 v[20:21], v[20:21], v[152:153]
	v_pk_add_f32 v[22:23], v[22:23], v[154:155]
	s_waitcnt vmcnt(2)
	v_pk_add_f32 v[24:25], v[24:25], v[156:157]
	v_pk_add_f32 v[26:27], v[26:27], v[158:159]
	s_waitcnt vmcnt(1)
	v_pk_add_f32 v[28:29], v[28:29], v[160:161]
	v_pk_add_f32 v[30:31], v[30:31], v[162:163]
	s_waitcnt vmcnt(0)
	v_pk_add_f32 v[32:33], v[32:33], v[164:165]
	v_pk_add_f32 v[34:35], v[34:35], v[166:167]
	global_load_dwordx4 v[136:139], v132, s[98:99] sc0 sc1
	v_add_u32_e32 v132, 0x2000, v132
	global_load_dwordx4 v[140:143], v132, s[98:99] sc0 sc1
	v_add_u32_e32 v132, 0x2000, v132
	global_load_dwordx4 v[144:147], v132, s[98:99] sc0 sc1
	v_add_u32_e32 v132, 0x2000, v132
	global_load_dwordx4 v[148:151], v132, s[98:99] sc0 sc1
	v_add_u32_e32 v132, 0x2000, v132
	global_load_dwordx4 v[152:155], v132, s[98:99] sc0 sc1
	v_add_u32_e32 v132, 0x2000, v132
	global_load_dwordx4 v[156:159], v132, s[98:99] sc0 sc1
	v_add_u32_e32 v132, 0x2000, v132
	global_load_dwordx4 v[160:163], v132, s[98:99] sc0 sc1
	v_add_u32_e32 v132, 0x2000, v132
	global_load_dwordx4 v[164:167], v132, s[98:99] sc0 sc1
	v_add_u32_e32 v132, 0x2000, v132
	s_waitcnt vmcnt(7)
	v_pk_add_f32 v[36:37], v[36:37], v[136:137]
	v_pk_add_f32 v[38:39], v[38:39], v[138:139]
	s_waitcnt vmcnt(6)
	v_pk_add_f32 v[40:41], v[40:41], v[140:141]
	v_pk_add_f32 v[42:43], v[42:43], v[142:143]
	s_waitcnt vmcnt(5)
	v_pk_add_f32 v[44:45], v[44:45], v[144:145]
	v_pk_add_f32 v[46:47], v[46:47], v[146:147]
	s_waitcnt vmcnt(4)
	v_pk_add_f32 v[48:49], v[48:49], v[148:149]
	v_pk_add_f32 v[50:51], v[50:51], v[150:151]
	s_waitcnt vmcnt(3)
	v_pk_add_f32 v[52:53], v[52:53], v[152:153]
	v_pk_add_f32 v[54:55], v[54:55], v[154:155]
	s_waitcnt vmcnt(2)
	v_pk_add_f32 v[56:57], v[56:57], v[156:157]
	v_pk_add_f32 v[58:59], v[58:59], v[158:159]
	s_waitcnt vmcnt(1)
	v_pk_add_f32 v[60:61], v[60:61], v[160:161]
	v_pk_add_f32 v[62:63], v[62:63], v[162:163]
	s_waitcnt vmcnt(0)
	v_pk_add_f32 v[64:65], v[64:65], v[164:165]
	v_pk_add_f32 v[66:67], v[66:67], v[166:167]
	global_load_dwordx4 v[136:139], v132, s[98:99] sc0 sc1
	v_add_u32_e32 v132, 0x2000, v132
	global_load_dwordx4 v[140:143], v132, s[98:99] sc0 sc1
	v_add_u32_e32 v132, 0x2000, v132
	global_load_dwordx4 v[144:147], v132, s[98:99] sc0 sc1
	v_add_u32_e32 v132, 0x2000, v132
	global_load_dwordx4 v[148:151], v132, s[98:99] sc0 sc1
	v_add_u32_e32 v132, 0x2000, v132
	global_load_dwordx4 v[152:155], v132, s[98:99] sc0 sc1
	v_add_u32_e32 v132, 0x2000, v132
	global_load_dwordx4 v[156:159], v132, s[98:99] sc0 sc1
	v_add_u32_e32 v132, 0x2000, v132
	global_load_dwordx4 v[160:163], v132, s[98:99] sc0 sc1
	v_add_u32_e32 v132, 0x2000, v132
	global_load_dwordx4 v[164:167], v132, s[98:99] sc0 sc1
	v_add_u32_e32 v132, 0x2000, v132
	s_waitcnt vmcnt(7)
	v_pk_add_f32 v[68:69], v[68:69], v[136:137]
	v_pk_add_f32 v[70:71], v[70:71], v[138:139]
	s_waitcnt vmcnt(6)
	v_pk_add_f32 v[72:73], v[72:73], v[140:141]
	v_pk_add_f32 v[74:75], v[74:75], v[142:143]
	s_waitcnt vmcnt(5)
	v_pk_add_f32 v[76:77], v[76:77], v[144:145]
	v_pk_add_f32 v[78:79], v[78:79], v[146:147]
	s_waitcnt vmcnt(4)
	v_pk_add_f32 v[80:81], v[80:81], v[148:149]
	v_pk_add_f32 v[82:83], v[82:83], v[150:151]
	s_waitcnt vmcnt(3)
	v_pk_add_f32 v[84:85], v[84:85], v[152:153]
	v_pk_add_f32 v[86:87], v[86:87], v[154:155]
	s_waitcnt vmcnt(2)
	v_pk_add_f32 v[88:89], v[88:89], v[156:157]
	v_pk_add_f32 v[90:91], v[90:91], v[158:159]
	s_waitcnt vmcnt(1)
	v_pk_add_f32 v[92:93], v[92:93], v[160:161]
	v_pk_add_f32 v[94:95], v[94:95], v[162:163]
	s_waitcnt vmcnt(0)
	v_pk_add_f32 v[96:97], v[96:97], v[164:165]
	v_pk_add_f32 v[98:99], v[98:99], v[166:167]
	global_load_dwordx4 v[136:139], v132, s[98:99] sc0 sc1
	v_add_u32_e32 v132, 0x2000, v132
	global_load_dwordx4 v[140:143], v132, s[98:99] sc0 sc1
	v_add_u32_e32 v132, 0x2000, v132
	global_load_dwordx4 v[144:147], v132, s[98:99] sc0 sc1
	v_add_u32_e32 v132, 0x2000, v132
	global_load_dwordx4 v[148:151], v132, s[98:99] sc0 sc1
	v_add_u32_e32 v132, 0x2000, v132
	global_load_dwordx4 v[152:155], v132, s[98:99] sc0 sc1
	v_add_u32_e32 v132, 0x2000, v132
	global_load_dwordx4 v[156:159], v132, s[98:99] sc0 sc1
	v_add_u32_e32 v132, 0x2000, v132
	global_load_dwordx4 v[160:163], v132, s[98:99] sc0 sc1
	v_add_u32_e32 v132, 0x2000, v132
	global_load_dwordx4 v[164:167], v132, s[98:99] sc0 sc1
	v_add_u32_e32 v132, 0x2000, v132
	s_waitcnt vmcnt(7)
; #define LAS __attribute__((address_space(3)))
; template <class Epi, int LDA, int LDB, int KK>
; __device__ __forceinline__ void gemm_phase(int wv, LAS unsigned char* lds, const Gemm g, const StaticOrder& S, const Epi& E) {
;     ...
;         E(acc, cur, wr, wc, fr, fq, (const LAS float*)(lds + 131072 + (ui % 3) * 1024));
	v_pk_add_f32 v[100:101], v[100:101], v[136:137]
	v_pk_add_f32 v[102:103], v[102:103], v[138:139]
	s_waitcnt vmcnt(6)
	v_pk_add_f32 v[104:105], v[104:105], v[140:141]
	v_pk_add_f32 v[106:107], v[106:107], v[142:143]
	s_waitcnt vmcnt(5)
	v_pk_add_f32 v[108:109], v[108:109], v[144:145]
	v_pk_add_f32 v[110:111], v[110:111], v[146:147]
	s_waitcnt vmcnt(4)
	v_pk_add_f32 v[112:113], v[112:113], v[148:149]
	v_pk_add_f32 v[114:115], v[114:115], v[150:151]
	s_waitcnt vmcnt(3)
	v_pk_add_f32 v[116:117], v[116:117], v[152:153]
	v_pk_add_f32 v[118:119], v[118:119], v[154:155]
	s_waitcnt vmcnt(2)
	v_pk_add_f32 v[120:121], v[120:121], v[156:157]
	v_pk_add_f32 v[122:123], v[122:123], v[158:159]
	s_waitcnt vmcnt(1)
	v_pk_add_f32 v[124:125], v[124:125], v[160:161]
	v_pk_add_f32 v[126:127], v[126:127], v[162:163]
	s_waitcnt vmcnt(0)
	v_pk_add_f32 v[128:129], v[128:129], v[164:165]
	v_pk_add_f32 v[130:131], v[130:131], v[166:167]
	global_load_dwordx4 v[136:139], v132, s[98:99] sc0 sc1
	v_add_u32_e32 v132, 0x2000, v132
	global_load_dwordx4 v[140:143], v132, s[98:99] sc0 sc1
	v_add_u32_e32 v132, 0x2000, v132
	global_load_dwordx4 v[144:147], v132, s[98:99] sc0 sc1
	v_add_u32_e32 v132, 0x2000, v132
	global_load_dwordx4 v[148:151], v132, s[98:99] sc0 sc1
	v_add_u32_e32 v132, 0x2000, v132
	global_load_dwordx4 v[152:155], v132, s[98:99] sc0 sc1
	v_add_u32_e32 v132, 0x2000, v132
	global_load_dwordx4 v[156:159], v132, s[98:99] sc0 sc1
	v_add_u32_e32 v132, 0x2000, v132
	global_load_dwordx4 v[160:163], v132, s[98:99] sc0 sc1
	v_add_u32_e32 v132, 0x2000, v132
	global_load_dwordx4 v[164:167], v132, s[98:99] sc0 sc1
	v_add_u32_e32 v132, 0x2000, v132
	s_waitcnt vmcnt(7)
	v_pk_add_f32 v[4:5], v[4:5], v[136:137]
	v_pk_add_f32 v[6:7], v[6:7], v[138:139]
	s_waitcnt vmcnt(6)
	v_pk_add_f32 v[8:9], v[8:9], v[140:141]
	v_pk_add_f32 v[10:11], v[10:11], v[142:143]
	s_waitcnt vmcnt(5)
	v_pk_add_f32 v[12:13], v[12:13], v[144:145]
	v_pk_add_f32 v[14:15], v[14:15], v[146:147]
	s_waitcnt vmcnt(4)
	v_pk_add_f32 v[16:17], v[16:17], v[148:149]
	v_pk_add_f32 v[18:19], v[18:19], v[150:151]
	s_waitcnt vmcnt(3)
	v_pk_add_f32 v[20:21], v[20:21], v[152:153]
	v_pk_add_f32 v[22:23], v[22:23], v[154:155]
	s_waitcnt vmcnt(2)
	v_pk_add_f32 v[24:25], v[24:25], v[156:157]
	v_pk_add_f32 v[26:27], v[26:27], v[158:159]
	s_waitcnt vmcnt(1)
	v_pk_add_f32 v[28:29], v[28:29], v[160:161]
	v_pk_add_f32 v[30:31], v[30:31], v[162:163]
	s_waitcnt vmcnt(0)
	v_pk_add_f32 v[32:33], v[32:33], v[164:165]
	v_pk_add_f32 v[34:35], v[34:35], v[166:167]
	global_load_dwordx4 v[136:139], v132, s[98:99] sc0 sc1
	v_add_u32_e32 v132, 0x2000, v132
	global_load_dwordx4 v[140:143], v132, s[98:99] sc0 sc1
	v_add_u32_e32 v132, 0x2000, v132
	global_load_dwordx4 v[144:147], v132, s[98:99] sc0 sc1
	v_add_u32_e32 v132, 0x2000, v132
	global_load_dwordx4 v[148:151], v132, s[98:99] sc0 sc1
	v_add_u32_e32 v132, 0x2000, v132
	global_load_dwordx4 v[152:155], v132, s[98:99] sc0 sc1
	v_add_u32_e32 v132, 0x2000, v132
	global_load_dwordx4 v[156:159], v132, s[98:99] sc0 sc1
	v_add_u32_e32 v132, 0x2000, v132
	global_load_dwordx4 v[160:163], v132, s[98:99] sc0 sc1
	v_add_u32_e32 v132, 0x2000, v132
	global_load_dwordx4 v[164:167], v132, s[98:99] sc0 sc1
	v_add_u32_e32 v132, 0x2000, v132
	s_waitcnt vmcnt(7)
	v_pk_add_f32 v[36:37], v[36:37], v[136:137]
	v_pk_add_f32 v[38:39], v[38:39], v[138:139]
	s_waitcnt vmcnt(6)
	v_pk_add_f32 v[40:41], v[40:41], v[140:141]
	v_pk_add_f32 v[42:43], v[42:43], v[142:143]
	s_waitcnt vmcnt(5)
	v_pk_add_f32 v[44:45], v[44:45], v[144:145]
	v_pk_add_f32 v[46:47], v[46:47], v[146:147]
	s_waitcnt vmcnt(4)
	v_pk_add_f32 v[48:49], v[48:49], v[148:149]
	v_pk_add_f32 v[50:51], v[50:51], v[150:151]
	s_waitcnt vmcnt(3)
	v_pk_add_f32 v[52:53], v[52:53], v[152:153]
	v_pk_add_f32 v[54:55], v[54:55], v[154:155]
	s_waitcnt vmcnt(2)
	v_pk_add_f32 v[56:57], v[56:57], v[156:157]
	v_pk_add_f32 v[58:59], v[58:59], v[158:159]
	s_waitcnt vmcnt(1)
	v_pk_add_f32 v[60:61], v[60:61], v[160:161]
	v_pk_add_f32 v[62:63], v[62:63], v[162:163]
	s_waitcnt vmcnt(0)
	v_pk_add_f32 v[64:65], v[64:65], v[164:165]
	v_pk_add_f32 v[66:67], v[66:67], v[166:167]
	global_load_dwordx4 v[136:139], v132, s[98:99] sc0 sc1
	v_add_u32_e32 v132, 0x2000, v132
	global_load_dwordx4 v[140:143], v132, s[98:99] sc0 sc1
	v_add_u32_e32 v132, 0x2000, v132
	global_load_dwordx4 v[144:147], v132, s[98:99] sc0 sc1
	v_add_u32_e32 v132, 0x2000, v132
	global_load_dwordx4 v[148:151], v132, s[98:99] sc0 sc1
	v_add_u32_e32 v132, 0x2000, v132
	global_load_dwordx4 v[152:155], v132, s[98:99] sc0 sc1
	v_add_u32_e32 v132, 0x2000, v132
	global_load_dwordx4 v[156:159], v132, s[98:99] sc0 sc1
	v_add_u32_e32 v132, 0x2000, v132
	global_load_dwordx4 v[160:163], v132, s[98:99] sc0 sc1
	v_add_u32_e32 v132, 0x2000, v132
	global_load_dwordx4 v[164:167], v132, s[98:99] sc0 sc1
	v_add_u32_e32 v132, 0x2000, v132
	s_waitcnt vmcnt(7)
	v_pk_add_f32 v[68:69], v[68:69], v[136:137]
	v_pk_add_f32 v[70:71], v[70:71], v[138:139]
	s_waitcnt vmcnt(6)
	v_pk_add_f32 v[72:73], v[72:73], v[140:141]
	v_pk_add_f32 v[74:75], v[74:75], v[142:143]
	s_waitcnt vmcnt(5)
	v_pk_add_f32 v[76:77], v[76:77], v[144:145]
	v_pk_add_f32 v[78:79], v[78:79], v[146:147]
	s_waitcnt vmcnt(4)
	v_pk_add_f32 v[80:81], v[80:81], v[148:149]
	v_pk_add_f32 v[82:83], v[82:83], v[150:151]
	s_waitcnt vmcnt(3)
	v_pk_add_f32 v[84:85], v[84:85], v[152:153]
	v_pk_add_f32 v[86:87], v[86:87], v[154:155]
	s_waitcnt vmcnt(2)
	v_pk_add_f32 v[88:89], v[88:89], v[156:157]
	v_pk_add_f32 v[90:91], v[90:91], v[158:159]
	s_waitcnt vmcnt(1)
	v_pk_add_f32 v[92:93], v[92:93], v[160:161]
	v_pk_add_f32 v[94:95], v[94:95], v[162:163]
	s_waitcnt vmcnt(0)
; #define LAS __attribute__((address_space(3)))
; template <class Epi, int LDA, int LDB, int KK>
; __device__ __forceinline__ void gemm_phase(int wv, LAS unsigned char* lds, const Gemm g, const StaticOrder& S, const Epi& E) {
;     ...
;         E(acc, cur, wr, wc, fr, fq, (const LAS float*)(lds + 131072 + (ui % 3) * 1024));
	v_pk_add_f32 v[96:97], v[96:97], v[164:165]
	v_pk_add_f32 v[98:99], v[98:99], v[166:167]
	global_load_dwordx4 v[136:139], v132, s[98:99] sc0 sc1
	v_add_u32_e32 v132, 0x2000, v132
	global_load_dwordx4 v[140:143], v132, s[98:99] sc0 sc1
	v_add_u32_e32 v132, 0x2000, v132
	global_load_dwordx4 v[144:147], v132, s[98:99] sc0 sc1
	v_add_u32_e32 v132, 0x2000, v132
	global_load_dwordx4 v[148:151], v132, s[98:99] sc0 sc1
	v_add_u32_e32 v132, 0x2000, v132
	global_load_dwordx4 v[152:155], v132, s[98:99] sc0 sc1
	v_add_u32_e32 v132, 0x2000, v132
	global_load_dwordx4 v[156:159], v132, s[98:99] sc0 sc1
	v_add_u32_e32 v132, 0x2000, v132
	global_load_dwordx4 v[160:163], v132, s[98:99] sc0 sc1
	v_add_u32_e32 v132, 0x2000, v132
	global_load_dwordx4 v[164:167], v132, s[98:99] sc0 sc1
	v_add_u32_e32 v132, 0x2000, v132
	s_waitcnt vmcnt(7)
	v_pk_add_f32 v[100:101], v[100:101], v[136:137]
	v_pk_add_f32 v[102:103], v[102:103], v[138:139]
	s_waitcnt vmcnt(6)
	v_pk_add_f32 v[104:105], v[104:105], v[140:141]
	v_pk_add_f32 v[106:107], v[106:107], v[142:143]
	s_waitcnt vmcnt(5)
	v_pk_add_f32 v[108:109], v[108:109], v[144:145]
	v_pk_add_f32 v[110:111], v[110:111], v[146:147]
	s_waitcnt vmcnt(4)
	v_pk_add_f32 v[112:113], v[112:113], v[148:149]
	v_pk_add_f32 v[114:115], v[114:115], v[150:151]
	s_waitcnt vmcnt(3)
	v_pk_add_f32 v[116:117], v[116:117], v[152:153]
	v_pk_add_f32 v[118:119], v[118:119], v[154:155]
	s_waitcnt vmcnt(2)
	v_pk_add_f32 v[120:121], v[120:121], v[156:157]
	v_pk_add_f32 v[122:123], v[122:123], v[158:159]
	s_waitcnt vmcnt(1)
	v_pk_add_f32 v[124:125], v[124:125], v[160:161]
	v_pk_add_f32 v[126:127], v[126:127], v[162:163]
	s_waitcnt vmcnt(0)
	v_pk_add_f32 v[128:129], v[128:129], v[164:165]
	v_pk_add_f32 v[130:131], v[130:131], v[166:167]
	global_load_dwordx4 v[136:139], v132, s[98:99] sc0 sc1
	v_add_u32_e32 v132, 0x2000, v132
	global_load_dwordx4 v[140:143], v132, s[98:99] sc0 sc1
	v_add_u32_e32 v132, 0x2000, v132
	global_load_dwordx4 v[144:147], v132, s[98:99] sc0 sc1
	v_add_u32_e32 v132, 0x2000, v132
	global_load_dwordx4 v[148:151], v132, s[98:99] sc0 sc1
	v_add_u32_e32 v132, 0x2000, v132
	global_load_dwordx4 v[152:155], v132, s[98:99] sc0 sc1
	v_add_u32_e32 v132, 0x2000, v132
	global_load_dwordx4 v[156:159], v132, s[98:99] sc0 sc1
	v_add_u32_e32 v132, 0x2000, v132
	global_load_dwordx4 v[160:163], v132, s[98:99] sc0 sc1
	v_add_u32_e32 v132, 0x2000, v132
	global_load_dwordx4 v[164:167], v132, s[98:99] sc0 sc1
	v_add_u32_e32 v132, 0x2000, v132
	s_waitcnt vmcnt(7)
	v_pk_add_f32 v[4:5], v[4:5], v[136:137]
	v_pk_add_f32 v[6:7], v[6:7], v[138:139]
	s_waitcnt vmcnt(6)
	v_pk_add_f32 v[8:9], v[8:9], v[140:141]
	v_pk_add_f32 v[10:11], v[10:11], v[142:143]
	s_waitcnt vmcnt(5)
	v_pk_add_f32 v[12:13], v[12:13], v[144:145]
	v_pk_add_f32 v[14:15], v[14:15], v[146:147]
	s_waitcnt vmcnt(4)
	v_pk_add_f32 v[16:17], v[16:17], v[148:149]
	v_pk_add_f32 v[18:19], v[18:19], v[150:151]
	s_waitcnt vmcnt(3)
	v_pk_add_f32 v[20:21], v[20:21], v[152:153]
	v_pk_add_f32 v[22:23], v[22:23], v[154:155]
	s_waitcnt vmcnt(2)
	v_pk_add_f32 v[24:25], v[24:25], v[156:157]
	v_pk_add_f32 v[26:27], v[26:27], v[158:159]
	s_waitcnt vmcnt(1)
	v_pk_add_f32 v[28:29], v[28:29], v[160:161]
	v_pk_add_f32 v[30:31], v[30:31], v[162:163]
	s_waitcnt vmcnt(0)
	v_pk_add_f32 v[32:33], v[32:33], v[164:165]
	v_pk_add_f32 v[34:35], v[34:35], v[166:167]
	global_load_dwordx4 v[136:139], v132, s[98:99] sc0 sc1
	v_add_u32_e32 v132, 0x2000, v132
	global_load_dwordx4 v[140:143], v132, s[98:99] sc0 sc1
	v_add_u32_e32 v132, 0x2000, v132
	global_load_dwordx4 v[144:147], v132, s[98:99] sc0 sc1
	v_add_u32_e32 v132, 0x2000, v132
	global_load_dwordx4 v[148:151], v132, s[98:99] sc0 sc1
	v_add_u32_e32 v132, 0x2000, v132
	global_load_dwordx4 v[152:155], v132, s[98:99] sc0 sc1
	v_add_u32_e32 v132, 0x2000, v132
	global_load_dwordx4 v[156:159], v132, s[98:99] sc0 sc1
	v_add_u32_e32 v132, 0x2000, v132
	global_load_dwordx4 v[160:163], v132, s[98:99] sc0 sc1
	v_add_u32_e32 v132, 0x2000, v132
	global_load_dwordx4 v[164:167], v132, s[98:99] sc0 sc1
	v_add_u32_e32 v132, 0x2000, v132
	s_waitcnt vmcnt(7)
	v_pk_add_f32 v[36:37], v[36:37], v[136:137]
	v_pk_add_f32 v[38:39], v[38:39], v[138:139]
	s_waitcnt vmcnt(6)
	v_pk_add_f32 v[40:41], v[40:41], v[140:141]
	v_pk_add_f32 v[42:43], v[42:43], v[142:143]
	s_waitcnt vmcnt(5)
	v_pk_add_f32 v[44:45], v[44:45], v[144:145]
	v_pk_add_f32 v[46:47], v[46:47], v[146:147]
	s_waitcnt vmcnt(4)
	v_pk_add_f32 v[48:49], v[48:49], v[148:149]
	v_pk_add_f32 v[50:51], v[50:51], v[150:151]
	s_waitcnt vmcnt(3)
	v_pk_add_f32 v[52:53], v[52:53], v[152:153]
	v_pk_add_f32 v[54:55], v[54:55], v[154:155]
	s_waitcnt vmcnt(2)
	v_pk_add_f32 v[56:57], v[56:57], v[156:157]
	v_pk_add_f32 v[58:59], v[58:59], v[158:159]
	s_waitcnt vmcnt(1)
	v_pk_add_f32 v[60:61], v[60:61], v[160:161]
	v_pk_add_f32 v[62:63], v[62:63], v[162:163]
	s_waitcnt vmcnt(0)
	v_pk_add_f32 v[64:65], v[64:65], v[164:165]
	v_pk_add_f32 v[66:67], v[66:67], v[166:167]
	global_load_dwordx4 v[136:139], v132, s[98:99] sc0 sc1
	v_add_u32_e32 v132, 0x2000, v132
	global_load_dwordx4 v[140:143], v132, s[98:99] sc0 sc1
	v_add_u32_e32 v132, 0x2000, v132
	global_load_dwordx4 v[144:147], v132, s[98:99] sc0 sc1
	v_add_u32_e32 v132, 0x2000, v132
	global_load_dwordx4 v[148:151], v132, s[98:99] sc0 sc1
	v_add_u32_e32 v132, 0x2000, v132
	global_load_dwordx4 v[152:155], v132, s[98:99] sc0 sc1
	v_add_u32_e32 v132, 0x2000, v132
	global_load_dwordx4 v[156:159], v132, s[98:99] sc0 sc1
	v_add_u32_e32 v132, 0x2000, v132
	global_load_dwordx4 v[160:163], v132, s[98:99] sc0 sc1
	v_add_u32_e32 v132, 0x2000, v132
	global_load_dwordx4 v[164:167], v132, s[98:99] sc0 sc1
	v_add_u32_e32 v132, 0x2000, v132
	s_waitcnt vmcnt(7)
; __device__ __forceinline__ float shx(float v, int mask, int lane) { return __int_as_float(__builtin_amdgcn_ds_bpermute((lane ^ mask) << 2, __float_as_int(v))); }
; __device__ __forceinline__ u32x4 pack8(const f32x4& a, const f32x4& b) { u32x4 w; w.x = pack2(a[0], a[1]); w.y = pack2(a[2], a[3]); w.z = pack2(b[0], b[1]); w.w = pack2(b[2], b[3]); return w; }
;     __device__ __forceinline__ void operator()(AccT& acc, const pg8::Unit& u, int wr, int wc, int fr, int fq, const LAS float* rs) const {
;         int row0 = u.pm * 256 + wr * 64 + fr; asm volatile("" : "+v"(row0)); const int cb = u.pn * 256 + wc * 32 + 8 * fq, lane = fr + 16 * fq;
; #pragma unroll
;         for (int ai = 0; ai < 2; ++ai) {
;             f32x4 hv[4][2][2];
; #pragma unroll
;             for (int m = 0; m < 4; ++m)
; #pragma unroll
;                 for (int bj = 0; bj < 2; ++bj) { const float* hp = h + (size_t)(row0 + ai * 128 + m * 16) * D + cb + bj * 128; hv[m][bj][0] = *(const f32x4*)hp; hv[m][bj][1] = *(const f32x4*)(hp + 4); }
; #pragma unroll
;             for (int m = 0; m < 4; ++m) {
;                 const int row = row0 + ai * 128 + m * 16; float ss = 0.f;
; #pragma unroll
;                 for (int bj = 0; bj < 2; ++bj) {
;                     const int col = cb + bj * 128; float* hp = h + (size_t)row * D + col;
;                     const f32x4 o0 = hv[m][bj][0] + acc[ai][bj][m][0], o1 = hv[m][bj][1] + acc[ai][bj][m][1];
;                     *(f32x4*)hp = o0; *(f32x4*)(hp + 4) = o1;
;                     *(u32x4*)(hb + (size_t)row * D + col) = pack8(o0, o1);
;                     ss += o0[0] * o0[0] + o0[1] * o0[1] + o0[2] * o0[2] + o0[3] * o0[3] + o1[0] * o1[0] + o1[1] * o1[1] + o1[2] * o1[2] + o1[3] * o1[3];
;                 }
;                 ss += shx(ss, 16, lane); ss += shx(ss, 32, lane);
;                 if (fq == 0) atomicAdd(rsqn + row, ss);
	v_pk_add_f32 v[68:69], v[68:69], v[136:137]
	v_pk_add_f32 v[70:71], v[70:71], v[138:139]
	s_waitcnt vmcnt(6)
	v_pk_add_f32 v[72:73], v[72:73], v[140:141]
	v_pk_add_f32 v[74:75], v[74:75], v[142:143]
	s_waitcnt vmcnt(5)
	v_pk_add_f32 v[76:77], v[76:77], v[144:145]
	v_pk_add_f32 v[78:79], v[78:79], v[146:147]
	s_waitcnt vmcnt(4)
	v_pk_add_f32 v[80:81], v[80:81], v[148:149]
	v_pk_add_f32 v[82:83], v[82:83], v[150:151]
	s_waitcnt vmcnt(3)
	v_pk_add_f32 v[84:85], v[84:85], v[152:153]
	v_pk_add_f32 v[86:87], v[86:87], v[154:155]
	s_waitcnt vmcnt(2)
	v_pk_add_f32 v[88:89], v[88:89], v[156:157]
	v_pk_add_f32 v[90:91], v[90:91], v[158:159]
	s_waitcnt vmcnt(1)
	v_pk_add_f32 v[92:93], v[92:93], v[160:161]
	v_pk_add_f32 v[94:95], v[94:95], v[162:163]
	s_waitcnt vmcnt(0)
	v_pk_add_f32 v[96:97], v[96:97], v[164:165]
	v_pk_add_f32 v[98:99], v[98:99], v[166:167]
	global_load_dwordx4 v[136:139], v132, s[98:99] sc0 sc1
	v_add_u32_e32 v132, 0x2000, v132
	global_load_dwordx4 v[140:143], v132, s[98:99] sc0 sc1
	v_add_u32_e32 v132, 0x2000, v132
	global_load_dwordx4 v[144:147], v132, s[98:99] sc0 sc1
	v_add_u32_e32 v132, 0x2000, v132
	global_load_dwordx4 v[148:151], v132, s[98:99] sc0 sc1
	v_add_u32_e32 v132, 0x2000, v132
	global_load_dwordx4 v[152:155], v132, s[98:99] sc0 sc1
	v_add_u32_e32 v132, 0x2000, v132
	global_load_dwordx4 v[156:159], v132, s[98:99] sc0 sc1
	v_add_u32_e32 v132, 0x2000, v132
	global_load_dwordx4 v[160:163], v132, s[98:99] sc0 sc1
	v_add_u32_e32 v132, 0x2000, v132
	global_load_dwordx4 v[164:167], v132, s[98:99] sc0 sc1
	s_waitcnt vmcnt(7)
	v_pk_add_f32 v[100:101], v[100:101], v[136:137]
	v_pk_add_f32 v[102:103], v[102:103], v[138:139]
	s_waitcnt vmcnt(6)
	v_pk_add_f32 v[104:105], v[104:105], v[140:141]
	v_pk_add_f32 v[106:107], v[106:107], v[142:143]
	s_waitcnt vmcnt(5)
	v_pk_add_f32 v[108:109], v[108:109], v[144:145]
	v_pk_add_f32 v[110:111], v[110:111], v[146:147]
	s_waitcnt vmcnt(4)
	v_pk_add_f32 v[112:113], v[112:113], v[148:149]
	v_pk_add_f32 v[114:115], v[114:115], v[150:151]
	s_waitcnt vmcnt(3)
	v_pk_add_f32 v[116:117], v[116:117], v[152:153]
	v_pk_add_f32 v[118:119], v[118:119], v[154:155]
	s_waitcnt vmcnt(2)
	v_pk_add_f32 v[120:121], v[120:121], v[156:157]
	v_pk_add_f32 v[122:123], v[122:123], v[158:159]
	s_waitcnt vmcnt(1)
	v_pk_add_f32 v[124:125], v[124:125], v[160:161]
	v_pk_add_f32 v[126:127], v[126:127], v[162:163]
	s_waitcnt vmcnt(0)
	v_pk_add_f32 v[128:129], v[128:129], v[164:165]
	v_pk_add_f32 v[130:131], v[130:131], v[166:167]
.Lot_epi:
	v_lshl_or_b32 v202, s23, 8, v233
	v_lshl_add_u32 v206, s22, 8, v197
	v_ashrrev_i32_e32 v203, 31, v202
	v_lshlrev_b64 v[244:245], 2, v[202:203]
	v_ashrrev_i32_e32 v207, 31, v206
	v_lshl_add_u64 v[204:205], s[10:11], 0, v[244:245]
	v_lshlrev_b64 v[246:247], 13, v[206:207]
	v_lshl_add_u64 v[132:133], v[204:205], 0, v[246:247]
	global_load_dwordx4 v[236:239], v[132:133], off offset:16
	global_load_dwordx4 v[240:243], v[132:133], off
	global_load_dwordx4 v[180:183], v[132:133], off offset:528
	global_load_dwordx4 v[184:187], v[132:133], off offset:512
	v_add_u32_e32 v214, 16, v206
	v_ashrrev_i32_e32 v215, 31, v214
	v_add_u32_e32 v210, 32, v206
	v_add_u32_e32 v208, 48, v206
	v_lshlrev_b64 v[218:219], 13, v[214:215]
	v_ashrrev_i32_e32 v211, 31, v210
	v_ashrrev_i32_e32 v209, 31, v208
	v_lshl_add_u64 v[132:133], v[204:205], 0, v[218:219]
	v_lshlrev_b64 v[216:217], 13, v[210:211]
	v_lshlrev_b64 v[212:213], 13, v[208:209]
	global_load_dwordx4 v[172:175], v[132:133], off offset:16
	global_load_dwordx4 v[176:179], v[132:133], off
	global_load_dwordx4 v[164:167], v[132:133], off offset:528
	global_load_dwordx4 v[168:171], v[132:133], off offset:512
	v_lshl_add_u64 v[132:133], v[204:205], 0, v[216:217]
	v_lshl_add_u64 v[136:137], v[204:205], 0, v[212:213]
	global_load_dwordx4 v[156:159], v[132:133], off offset:16
	global_load_dwordx4 v[160:163], v[132:133], off
	global_load_dwordx4 v[140:143], v[132:133], off offset:528
	global_load_dwordx4 v[148:151], v[132:133], off offset:512
	global_load_dwordx4 v[144:147], v[136:137], off offset:16
	global_load_dwordx4 v[152:155], v[136:137], off
	s_nop 0
	global_load_dwordx4 v[132:135], v[136:137], off offset:528
	s_nop 0
	global_load_dwordx4 v[136:139], v[136:137], off offset:512
	v_lshl_add_u64 v[246:247], s[10:11], 0, v[246:247]
	v_lshl_add_u64 v[244:245], v[246:247], 0, v[244:245]
	s_waitcnt vmcnt(0)
	v_pk_add_f32 v[126:127], v[126:127], v[238:239]
	v_pk_add_f32 v[130:131], v[130:131], v[242:243]
	v_pk_add_f32 v[128:129], v[128:129], v[240:241]
	v_pk_add_f32 v[124:125], v[124:125], v[236:237]
	global_store_dwordx4 v[244:245], v[128:131], off
	global_store_dwordx4 v[244:245], v[124:127], off offset:16
	v_cvt_pk_bf16_f32 v236, v128, v129
	v_lshlrev_b64 v[240:241], 12, v[206:207]
	v_mul_f32_e32 v129, v129, v129
	v_fmac_f32_e32 v129, v128, v128
	v_lshl_add_u64 v[240:241], s[8:9], 0, v[240:241]
	v_fmac_f32_e32 v129, v130, v130
	v_lshl_add_u64 v[240:241], v[202:203], 1, v[240:241]
	v_fmac_f32_e32 v129, v131, v131
	v_pk_add_f32 v[122:123], v[122:123], v[186:187]
	v_pk_add_f32 v[120:121], v[120:121], v[184:185]
	v_cvt_pk_bf16_f32 v237, v130, v131
	v_cvt_pk_bf16_f32 v238, v124, v125
	v_cvt_pk_bf16_f32 v239, v126, v127
	global_store_dwordx4 v[240:241], v[236:239], off
	v_fmac_f32_e32 v129, v124, v124
	v_pk_add_f32 v[118:119], v[118:119], v[182:183]
	v_pk_add_f32 v[116:117], v[116:117], v[180:181]
	global_store_dwordx4 v[244:245], v[120:123], off offset:512
	global_store_dwordx4 v[244:245], v[116:119], off offset:528
	v_cvt_pk_bf16_f32 v124, v120, v121
	v_fmac_f32_e32 v129, v125, v125
	v_mul_f32_e32 v121, v121, v121
	v_fmac_f32_e32 v121, v120, v120
	v_fmac_f32_e32 v121, v122, v122
	v_fmac_f32_e32 v121, v123, v123
	v_fmac_f32_e32 v121, v116, v116
	v_fmac_f32_e32 v121, v117, v117
	v_fmac_f32_e32 v129, v126, v126
	v_fmac_f32_e32 v121, v118, v118
	v_fmac_f32_e32 v129, v127, v127
	v_fmac_f32_e32 v121, v119, v119
	v_cvt_pk_bf16_f32 v126, v116, v117
	v_add_f32_e32 v116, v129, v121
	ds_bpermute_b32 v117, v231, v116
	v_cvt_pk_bf16_f32 v125, v122, v123
	v_cvt_pk_bf16_f32 v127, v118, v119
	global_store_dwordx4 v[240:241], v[124:127], off offset:256
	s_waitcnt lgkmcnt(0)
	v_add_f32_e32 v116, v116, v117
	ds_bpermute_b32 v117, v232, v116
	s_and_saveexec_b64 s[22:23], s[4:5]
	s_cbranch_execz .LBB0_625
	s_waitcnt lgkmcnt(0)
	v_add_f32_e32 v118, v116, v117
	v_lshl_add_u64 v[116:117], v[206:207], 2, s[12:13]
	global_atomic_add_f32 v[116:117], v118, off
